# v3 + loop-invariant fragment address math hoisted out of the tile loop
# speedup vs baseline: 1.0022x; 1.0002x over previous
.LBB0_529:
	v_mov_b32_e32 v0, v1
	s_ashr_i32 s43, s39, 3
	v_mbcnt_lo_u32_b32 v0, -1, v0
	v_mbcnt_hi_u32_b32 v0, -1, v0
	v_add_u32_e32 v138, s54, v0
	s_sub_i32 s21, 63, s43
	v_readfirstlane_b32 s22, v138
	s_ashr_i32 s23, s22, 6
	s_lshl_b32 s8, s21, 8
	s_lshl_b32 s6, s23, 5
	s_and_b32 s9, s39, 7
	v_and_b32_e32 v215, 31, v138
	s_add_i32 s20, s6, s8
	v_or_b32_e32 v2, s20, v215
	v_mov_b64_e32 v[4:5], s[70:71]
	s_mul_i32 s45, s9, 0xc0
	v_bfe_u32 v214, v138, 5, 1
	v_mad_i64_i32 v[4:5], s[10:11], v2, s46, v[4:5]
	s_lshl_b32 s86, s45, 1
	v_ashrrev_i32_e32 v3, 31, v2
	v_lshl_add_u64 v[4:5], v[4:5], 0, s[86:87]
	v_lshlrev_b32_e32 v0, 4, v214
	v_lshl_add_u64 v[4:5], v[4:5], 0, v[0:1]
	v_lshl_add_u64 v[2:3], v[2:3], 2, s[68:69]
	global_load_dwordx4 v[110:113], v[4:5], off
	global_load_dwordx4 v[106:109], v[4:5], off offset:32
	global_load_dwordx4 v[102:105], v[4:5], off offset:64
	global_load_dwordx4 v[98:101], v[4:5], off offset:96
	global_load_dwordx4 v[94:97], v[4:5], off offset:128
	global_load_dwordx4 v[90:93], v[4:5], off offset:160
	global_load_dwordx4 v[86:89], v[4:5], off offset:192
	global_load_dwordx4 v[82:85], v[4:5], off offset:224
	global_load_dwordx4 v[78:81], v[4:5], off offset:256
	global_load_dwordx4 v[118:121], v[4:5], off offset:288
	global_load_dwordx4 v[74:77], v[4:5], off offset:320
	global_load_dwordx4 v[114:117], v[4:5], off offset:352
	global_load_dword v142, v[2:3], off
	v_and_b32_e32 v2, 64, v233
	v_and_b32_e32 v212, 32, v138
	v_add_u32_e32 v216, 64, v2
	global_load_dwordx4 v[2:5], v212, s[24:25] offset:16
	global_load_dwordx4 v[6:9], v212, s[24:25]
	global_load_dwordx4 v[10:13], v212, s[24:25] offset:80
	global_load_dwordx4 v[14:17], v212, s[24:25] offset:64
	global_load_dwordx4 v[122:125], v212, s[26:27] offset:256
	global_load_dwordx4 v[18:21], v212, s[24:25] offset:144
	global_load_dwordx4 v[22:25], v212, s[24:25] offset:128
	global_load_dwordx4 v[126:129], v212, s[26:27] offset:240
	global_load_dwordx4 v[26:29], v212, s[24:25] offset:208
	global_load_dwordx4 v[30:33], v212, s[24:25] offset:192
	global_load_dwordx4 v[34:37], v212, s[24:25] offset:272
	global_load_dwordx4 v[38:41], v212, s[24:25] offset:256
	global_load_dwordx4 v[42:45], v212, s[24:25] offset:336
	global_load_dwordx4 v[46:49], v212, s[24:25] offset:320
	global_load_dwordx4 v[50:53], v212, s[24:25] offset:384
	global_load_dwordx4 v[54:57], v212, s[24:25] offset:512
	global_load_dwordx4 v[130:133], v212, s[26:27] offset:192
	global_load_dwordx4 v[134:137], v212, s[26:27] offset:176
	global_load_dwordx4 v[58:61], v212, s[24:25] offset:576
	global_load_dwordx4 v[70:73], v212, s[24:25] offset:592
	global_load_dwordx4 v[62:65], v212, s[24:25] offset:704
	global_load_dwordx4 v[66:69], v212, s[24:25] offset:720
	v_xor_b32_e32 v0, 32, v233
	v_cmp_lt_i32_e32 vcc, v0, v216
	s_lshl_b32 s10, s23, 2
	v_bfe_u32 v140, v138, 3, 1
	v_cndmask_b32_e32 v0, v233, v0, vcc
	v_lshlrev_b32_e32 v231, 2, v0
	v_bfe_u32 v0, v138, 4, 2
	v_or_b32_e32 v139, s10, v0
	v_lshlrev_b32_e32 v141, 1, v139
	v_and_b32_e32 v217, 63, v138
	v_bitop3_b32 v0, s10, v138, v0 bitop3:0x36
	v_or_b32_e32 v143, v141, v140
	v_mov_b64_e32 v[138:139], s[66:67]
	v_mad_i64_i32 v[138:139], s[10:11], v143, s46, v[138:139]
	v_lshlrev_b32_e32 v0, 4, v0
	v_lshl_add_u64 v[138:139], v[138:139], 0, s[86:87]
	v_and_b32_e32 v0, 0x70, v0
	s_lshl_b32 s44, s9, 7
	v_lshl_add_u64 v[180:181], v[138:139], 0, v[0:1]
	v_add_u32_e32 v138, s44, v141
	s_lshl_b32 s9, s23, 10
	v_or_b32_e32 v138, v138, v140
	s_add_i32 s9, s9, 0
	v_ashrrev_i32_e32 v139, 31, v138
	s_mov_b32 m0, s9
	v_lshlrev_b64 v[138:139], 15, v[138:139]
	global_load_lds_dwordx4 v[180:181], off
	v_lshl_add_u64 v[140:141], v[180:181], 0, s[94:95]
	s_add_i32 m0, s9, 0x2000
	v_lshl_add_u64 v[138:139], s[12:13], 0, v[138:139]
	global_load_lds_dwordx4 v[140:141], off
	v_lshl_add_u64 v[140:141], v[180:181], 0, s[96:97]
	s_add_i32 m0, s9, 0x4000
	v_lshl_add_u64 v[182:183], v[138:139], 0, v[0:1]
	global_load_lds_dwordx4 v[140:141], off
	s_add_i32 m0, s9, 0x6000
	v_lshl_add_u64 v[138:139], v[182:183], 0, s[92:93]
	global_load_lds_dwordx4 v[182:183], off
	s_add_i32 m0, s9, 0x8000
	s_mov_b64 s[10:11], 0x30000
	global_load_lds_dwordx4 v[138:139], off
	v_lshl_add_u64 v[138:139], v[180:181], 0, s[10:11]
	s_add_i32 m0, s9, 0xa000
	s_mov_b64 s[10:11], 0x30080
	global_load_lds_dwordx4 v[138:139], off
	v_lshl_add_u64 v[138:139], v[180:181], 0, s[10:11]
	s_add_i32 m0, s9, 0xc000
	s_mov_b64 s[10:11], 0x30100
	global_load_lds_dwordx4 v[138:139], off
	v_lshl_add_u64 v[138:139], v[180:181], 0, s[10:11]
	s_add_i32 m0, s9, 0xe000
	s_mov_b64 s[10:11], 0x200080
	global_load_lds_dwordx4 v[138:139], off
	s_add_i32 m0, s9, 0x10000
	v_lshl_add_u64 v[138:139], v[182:183], 0, s[94:95]
	global_load_lds_dwordx4 v[138:139], off
	v_lshl_add_u64 v[138:139], v[182:183], 0, s[10:11]
	s_add_i32 m0, s9, 0x12000
	s_waitcnt vmcnt(0)
	v_lshlrev_b32_e32 v148, 16, v107
	global_load_lds_dwordx4 v[138:139], off
	v_and_b32_e32 v149, 0xffff0000, v107
	v_and_b32_e32 v195, 0xffff0000, v121
	v_and_b32_e32 v203, 0xffff0000, v120
	v_lshlrev_b32_e32 v194, 16, v121
	v_cvt_f32_i32_e32 v0, v142
	v_lshlrev_b32_e32 v202, 16, v120
	v_and_b32_e32 v189, 0xffff0000, v117
	v_mov_b32_e32 v120, v194
	v_mul_f32_e32 v125, v125, v0
	v_cvt_f64_f32_e32 v[138:139], v125
	v_mul_f64 v[140:141], v[138:139], s[84:85]
	v_rndne_f64_e32 v[140:141], v[140:141]
	v_fma_f64 v[138:139], v[138:139], s[84:85], -v[140:141]
	v_cvt_f32_f64_e32 v125, v[138:139]
	v_mul_f32_e32 v124, v124, v0
	v_cos_f32_e32 v145, v125
	v_sin_f32_e32 v147, v125
	v_cvt_f64_f32_e32 v[124:125], v124
	v_mul_f64 v[138:139], v[124:125], s[84:85]
	v_rndne_f64_e32 v[138:139], v[138:139]
	v_fma_f64 v[124:125], v[124:125], s[84:85], -v[138:139]
	v_cvt_f32_f64_e32 v124, v[124:125]
	v_mul_f32_e32 v123, v123, v0
	v_sin_f32_e32 v146, v124
	v_cos_f32_e32 v144, v124
	v_cvt_f64_f32_e32 v[124:125], v123
	v_mul_f64 v[138:139], v[124:125], s[84:85]
	v_rndne_f64_e32 v[138:139], v[138:139]
	v_fma_f64 v[124:125], v[124:125], s[84:85], -v[138:139]
	v_cvt_f32_f64_e32 v123, v[124:125]
	v_mul_f32_e32 v122, v122, v0
	v_sin_f32_e32 v155, v123
	v_cos_f32_e32 v143, v123
	v_cvt_f64_f32_e32 v[122:123], v122
	v_mul_f64 v[124:125], v[122:123], s[84:85]
	v_rndne_f64_e32 v[124:125], v[124:125]
	v_fma_f64 v[122:123], v[122:123], s[84:85], -v[124:125]
	v_cvt_f32_f64_e32 v122, v[122:123]
	v_sin_f32_e32 v154, v122
	v_cos_f32_e32 v142, v122
	v_mul_f32_e32 v122, v129, v0
	v_cvt_f64_f32_e32 v[122:123], v122
	v_mul_f64 v[124:125], v[122:123], s[84:85]
	v_rndne_f64_e32 v[124:125], v[124:125]
	v_fma_f64 v[122:123], v[122:123], s[84:85], -v[124:125]
	v_cvt_f32_f64_e32 v122, v[122:123]
	v_sin_f32_e32 v151, v122
	v_cos_f32_e32 v153, v122
	v_mul_f32_e32 v122, v128, v0
	v_cvt_f64_f32_e32 v[122:123], v122
	v_mul_f64 v[124:125], v[122:123], s[84:85]
	v_rndne_f64_e32 v[124:125], v[124:125]
	v_fma_f64 v[122:123], v[122:123], s[84:85], -v[124:125]
	v_cvt_f32_f64_e32 v122, v[122:123]
	v_sin_f32_e32 v150, v122
	v_cos_f32_e32 v152, v122
	v_mul_f32_e32 v122, v127, v0
	v_cvt_f64_f32_e32 v[122:123], v122
	v_mul_f64 v[124:125], v[122:123], s[84:85]
	v_rndne_f64_e32 v[124:125], v[124:125]
	v_fma_f64 v[122:123], v[122:123], s[84:85], -v[124:125]
	v_cvt_f32_f64_e32 v122, v[122:123]
	v_sin_f32_e32 v161, v122
	v_cos_f32_e32 v159, v122
	v_mul_f32_e32 v122, v126, v0
	v_cvt_f64_f32_e32 v[122:123], v122
	v_mul_f64 v[124:125], v[122:123], s[84:85]
	v_rndne_f64_e32 v[124:125], v[124:125]
	v_fma_f64 v[122:123], v[122:123], s[84:85], -v[124:125]
	v_cvt_f32_f64_e32 v122, v[122:123]
	v_sin_f32_e32 v160, v122
	v_cos_f32_e32 v158, v122
	v_mul_f32_e32 v122, v134, v0
	v_cvt_f64_f32_e32 v[122:123], v122
	v_mul_f64 v[124:125], v[122:123], s[84:85]
	v_rndne_f64_e32 v[124:125], v[124:125]
	v_fma_f64 v[122:123], v[122:123], s[84:85], -v[124:125]
	v_cvt_f32_f64_e32 v122, v[122:123]
	v_mul_f32_e32 v123, v135, v0
	v_cvt_f64_f32_e32 v[126:127], v123
	v_mul_f64 v[128:129], v[126:127], s[84:85]
	v_rndne_f64_e32 v[128:129], v[128:129]
	v_fma_f64 v[126:127], v[126:127], s[84:85], -v[128:129]
	v_cvt_f32_f64_e32 v123, v[126:127]
	v_mul_f32_e32 v126, v136, v0
	v_cvt_f64_f32_e32 v[126:127], v126
	v_mul_f64 v[128:129], v[126:127], s[84:85]
	v_rndne_f64_e32 v[128:129], v[128:129]
	v_fma_f64 v[126:127], v[126:127], s[84:85], -v[128:129]
	v_cvt_f32_f64_e32 v126, v[126:127]
	v_mul_f32_e32 v127, v137, v0
	v_cvt_f64_f32_e32 v[134:135], v127
	v_mul_f64 v[136:137], v[134:135], s[84:85]
	v_rndne_f64_e32 v[136:137], v[136:137]
	v_fma_f64 v[134:135], v[134:135], s[84:85], -v[136:137]
	v_mul_f32_e32 v130, v130, v0
	v_cvt_f32_f64_e32 v127, v[134:135]
	v_cvt_f64_f32_e32 v[134:135], v130
	v_mul_f64 v[136:137], v[134:135], s[84:85]
	v_rndne_f64_e32 v[136:137], v[136:137]
	v_mul_f32_e32 v130, v131, v0
	v_fma_f64 v[134:135], v[134:135], s[84:85], -v[136:137]
	v_cvt_f64_f32_e32 v[130:131], v130
	v_cvt_f32_f64_e32 v213, v[134:135]
	v_mul_f64 v[134:135], v[130:131], s[84:85]
	v_rndne_f64_e32 v[134:135], v[134:135]
	v_fma_f64 v[204:205], v[130:131], s[84:85], -v[134:135]
	v_mov_b32_e32 v130, v195
	v_mov_b32_e32 v131, v203
	v_mov_b32_e32 v121, v202
	v_pk_mul_f32 v[130:131], v[130:131], v[130:131]
	v_and_b32_e32 v199, 0xffff0000, v116
	v_lshlrev_b32_e32 v188, 16, v117
	v_pk_fma_f32 v[208:209], v[120:121], v[120:121], v[130:131]
	v_lshlrev_b32_e32 v198, 16, v116
	v_mov_b32_e32 v120, v189
	v_mov_b32_e32 v121, v199
	v_mov_b32_e32 v116, v188
	v_mov_b32_e32 v117, v198
	v_pk_mul_f32 v[120:121], v[120:121], v[120:121]
	v_and_b32_e32 v193, 0xffff0000, v115
	v_and_b32_e32 v201, 0xffff0000, v114
	v_pk_fma_f32 v[206:207], v[116:117], v[116:117], v[120:121]
	v_lshlrev_b32_e32 v192, 16, v115
	v_lshlrev_b32_e32 v200, 16, v114
	v_mov_b32_e32 v116, v193
	v_mov_b32_e32 v117, v201
	v_mov_b32_e32 v114, v192
	v_mov_b32_e32 v115, v200
	v_pk_mul_f32 v[116:117], v[116:117], v[116:117]
	v_mul_f32_e32 v230, v132, v0
	v_mul_f32_e32 v237, v133, v0
	v_pk_fma_f32 v[210:211], v[114:115], v[114:115], v[116:117]
	v_lshlrev_b32_e32 v136, 16, v113
	v_and_b32_e32 v137, 0xffff0000, v113
	v_lshlrev_b32_e32 v134, 16, v112
	v_and_b32_e32 v135, 0xffff0000, v112
	v_lshlrev_b32_e32 v138, 16, v111
	v_and_b32_e32 v139, 0xffff0000, v111
	v_lshlrev_b32_e32 v132, 16, v110
	v_and_b32_e32 v133, 0xffff0000, v110
	v_lshlrev_b32_e32 v140, 16, v109
	v_and_b32_e32 v141, 0xffff0000, v109
	v_lshlrev_b32_e32 v130, 16, v108
	v_and_b32_e32 v131, 0xffff0000, v108
	v_lshlrev_b32_e32 v156, 16, v106
	v_and_b32_e32 v157, 0xffff0000, v106
	v_lshlrev_b32_e32 v162, 16, v105
	v_and_b32_e32 v163, 0xffff0000, v105
	v_lshlrev_b32_e32 v164, 16, v104
	v_and_b32_e32 v165, 0xffff0000, v104
	v_lshlrev_b32_e32 v170, 16, v101
	v_and_b32_e32 v171, 0xffff0000, v101
	v_lshlrev_b32_e32 v186, 16, v95
	v_and_b32_e32 v187, 0xffff0000, v95
	v_lshlrev_b32_e32 v116, 16, v94
	v_and_b32_e32 v117, 0xffff0000, v94
	v_lshlrev_b32_e32 v94, 16, v93
	v_and_b32_e32 v95, 0xffff0000, v93
	v_lshlrev_b32_e32 v114, 16, v92
	v_and_b32_e32 v115, 0xffff0000, v92
	v_lshlrev_b32_e32 v92, 16, v91
	v_and_b32_e32 v93, 0xffff0000, v91
	v_lshlrev_b32_e32 v112, 16, v90
	v_and_b32_e32 v113, 0xffff0000, v90
	v_lshlrev_b32_e32 v90, 16, v89
	v_and_b32_e32 v91, 0xffff0000, v89
	v_lshlrev_b32_e32 v110, 16, v88
	v_and_b32_e32 v111, 0xffff0000, v88
	v_lshlrev_b32_e32 v88, 16, v87
	v_and_b32_e32 v89, 0xffff0000, v87
	v_lshlrev_b32_e32 v108, 16, v86
	v_and_b32_e32 v109, 0xffff0000, v86
	v_lshlrev_b32_e32 v86, 16, v85
	v_and_b32_e32 v87, 0xffff0000, v85
	v_lshlrev_b32_e32 v106, 16, v84
	v_and_b32_e32 v107, 0xffff0000, v84
	v_lshlrev_b32_e32 v84, 16, v83
	v_and_b32_e32 v85, 0xffff0000, v83
	v_lshlrev_b32_e32 v104, 16, v82
	v_and_b32_e32 v105, 0xffff0000, v82
	v_lshlrev_b32_e32 v82, 16, v81
	v_and_b32_e32 v83, 0xffff0000, v81
	v_and_b32_e32 v101, 0xffff0000, v77
	v_and_b32_e32 v81, 0xffff0000, v76
	v_lshlrev_b32_e32 v190, 16, v119
	v_and_b32_e32 v191, 0xffff0000, v119
	v_lshlrev_b32_e32 v196, 16, v118
	v_and_b32_e32 v197, 0xffff0000, v118
	v_lshlrev_b32_e32 v172, 16, v100
	v_and_b32_e32 v173, 0xffff0000, v100
	v_lshlrev_b32_e32 v174, 16, v99
	v_and_b32_e32 v175, 0xffff0000, v99
	v_lshlrev_b32_e32 v120, 16, v98
	v_and_b32_e32 v121, 0xffff0000, v98
	v_lshlrev_b32_e32 v184, 16, v97
	v_and_b32_e32 v185, 0xffff0000, v97
	v_lshlrev_b32_e32 v118, 16, v96
	v_and_b32_e32 v119, 0xffff0000, v96
	v_lshlrev_b32_e32 v100, 16, v77
	v_lshlrev_b32_e32 v98, 16, v80
	v_and_b32_e32 v99, 0xffff0000, v80
	v_lshlrev_b32_e32 v80, 16, v76
	v_mov_b32_e32 v96, v101
	v_mov_b32_e32 v97, v81
	v_mov_b32_e32 v76, v100
	v_mov_b32_e32 v77, v80
	v_pk_mul_f32 v[96:97], v[96:97], v[96:97]
	v_and_b32_e32 v179, 0xffff0000, v74
	v_pk_fma_f32 v[96:97], v[76:77], v[76:77], v[96:97]
	v_lshlrev_b32_e32 v76, 16, v79
	v_and_b32_e32 v77, 0xffff0000, v79
	v_and_b32_e32 v79, 0xffff0000, v75
	v_lshlrev_b32_e32 v166, 16, v103
	v_and_b32_e32 v167, 0xffff0000, v103
	v_lshlrev_b32_e32 v168, 16, v102
	v_and_b32_e32 v169, 0xffff0000, v102
	v_lshlrev_b32_e32 v102, 16, v78
	v_and_b32_e32 v103, 0xffff0000, v78
	v_lshlrev_b32_e32 v78, 16, v75
	v_lshlrev_b32_e32 v178, 16, v74
	v_mov_b32_e32 v218, v79
	v_mov_b32_e32 v219, v179
	v_pk_mul_f32 v[176:177], v[136:137], v[136:137]
	v_mov_b32_e32 v74, v78
	v_mov_b32_e32 v75, v178
	v_pk_mul_f32 v[218:219], v[218:219], v[218:219]
	v_add_f32_e32 v0, v176, v177
	v_pk_fma_f32 v[74:75], v[74:75], v[74:75], v[218:219]
	v_pk_mul_f32 v[218:219], v[138:139], v[138:139]
	v_pk_mul_f32 v[176:177], v[132:133], v[132:133]
	v_add_f32_e32 v218, v218, v219
	v_add_f32_e32 v219, v176, v177
	v_pk_mul_f32 v[176:177], v[134:135], v[134:135]
	v_add_f32_e32 v218, v219, v218
	v_add_f32_e32 v219, v176, v177
	v_add_f32_e32 v218, v219, v218
	v_add_f32_e32 v0, v0, v218
	v_pk_mul_f32 v[218:219], v[156:157], v[156:157]
	v_pk_mul_f32 v[176:177], v[190:191], v[190:191]
	v_add_f32_e32 v218, v218, v219
	v_add_f32_e32 v0, v218, v0
	v_pk_mul_f32 v[218:219], v[148:149], v[148:149]
	v_add_f32_e32 v176, v176, v177
	v_add_f32_e32 v218, v218, v219
	v_add_f32_e32 v0, v218, v0
	v_pk_mul_f32 v[218:219], v[130:131], v[130:131]
	v_mov_b32_e32 v238, v228
	v_add_f32_e32 v218, v218, v219
	v_add_f32_e32 v0, v218, v0
	v_pk_mul_f32 v[218:219], v[140:141], v[140:141]
	global_load_dwordx4 v[226:229], v212, s[24:25] offset:656
	v_add_f32_e32 v218, v218, v219
	v_add_f32_e32 v0, v218, v0
	v_pk_mul_f32 v[218:219], v[168:169], v[168:169]
	global_load_dwordx4 v[222:225], v212, s[24:25] offset:528
	v_add_f32_e32 v218, v218, v219
	v_add_f32_e32 v0, v218, v0
	v_pk_mul_f32 v[218:219], v[166:167], v[166:167]
	v_cvt_f32_f64_e32 v204, v[204:205]
	v_add_f32_e32 v218, v218, v219
	v_add_f32_e32 v0, v218, v0
	v_pk_mul_f32 v[218:219], v[164:165], v[164:165]
	v_cos_f32_e32 v235, v204
	v_add_f32_e32 v218, v218, v219
	v_add_f32_e32 v0, v218, v0
	v_pk_mul_f32 v[218:219], v[162:163], v[162:163]
	v_cos_f32_e32 v234, v213
	v_add_f32_e32 v218, v218, v219
	v_add_f32_e32 v0, v218, v0
	v_pk_mul_f32 v[218:219], v[120:121], v[120:121]
	v_sin_f32_e32 v124, v122
	v_add_f32_e32 v218, v218, v219
	v_add_f32_e32 v0, v218, v0
	v_pk_mul_f32 v[218:219], v[174:175], v[174:175]
	v_cos_f32_e32 v122, v122
	v_add_f32_e32 v218, v218, v219
	v_add_f32_e32 v0, v218, v0
	v_pk_mul_f32 v[218:219], v[172:173], v[172:173]
	v_sin_f32_e32 v125, v123
	v_add_f32_e32 v218, v218, v219
	v_add_f32_e32 v0, v218, v0
	v_pk_mul_f32 v[218:219], v[170:171], v[170:171]
	v_cos_f32_e32 v123, v123
	v_add_f32_e32 v218, v218, v219
	v_add_f32_e32 v0, v218, v0
	v_pk_mul_f32 v[218:219], v[116:117], v[116:117]
	v_sin_f32_e32 v128, v126
	v_add_f32_e32 v218, v218, v219
	v_add_f32_e32 v0, v218, v0
	v_pk_mul_f32 v[218:219], v[186:187], v[186:187]
	v_cos_f32_e32 v126, v126
	v_add_f32_e32 v218, v218, v219
	v_add_f32_e32 v0, v218, v0
	v_pk_mul_f32 v[218:219], v[118:119], v[118:119]
	v_sin_f32_e32 v129, v127
	v_add_f32_e32 v218, v218, v219
	v_add_f32_e32 v0, v218, v0
	v_pk_mul_f32 v[218:219], v[184:185], v[184:185]
	v_cos_f32_e32 v127, v127
	v_add_f32_e32 v218, v218, v219
	v_add_f32_e32 v0, v218, v0
	v_pk_mul_f32 v[218:219], v[112:113], v[112:113]
	s_lshl_b32 s28, s21, 2
	v_add_f32_e32 v218, v218, v219
	v_add_f32_e32 v0, v218, v0
	v_pk_mul_f32 v[218:219], v[92:93], v[92:93]
	s_ashr_i32 s21, s22, 7
	v_add_f32_e32 v218, v218, v219
	v_add_f32_e32 v0, v218, v0
	v_pk_mul_f32 v[218:219], v[114:115], v[114:115]
	s_mov_b32 s0, 0
	v_add_f32_e32 v218, v218, v219
	v_add_f32_e32 v0, v218, v0
	v_pk_mul_f32 v[218:219], v[94:95], v[94:95]
	s_mov_b32 s7, 2
	v_add_f32_e32 v218, v218, v219
	v_add_f32_e32 v0, v218, v0
	v_pk_mul_f32 v[218:219], v[108:109], v[108:109]
	s_add_i32 s21, s21, s28
	v_add_f32_e32 v218, v218, v219
	v_add_f32_e32 v0, v218, v0
	v_pk_mul_f32 v[218:219], v[88:89], v[88:89]
	s_add_i32 s28, s28, 4
	v_add_f32_e32 v218, v218, v219
	v_add_f32_e32 v0, v218, v0
	v_pk_mul_f32 v[218:219], v[110:111], v[110:111]
	s_movk_i32 s86, 0x80
	v_add_f32_e32 v218, v218, v219
	v_add_f32_e32 v0, v218, v0
	v_pk_mul_f32 v[218:219], v[90:91], v[90:91]
	s_mov_b32 s33, 0
	v_add_f32_e32 v218, v218, v219
	v_add_f32_e32 v0, v218, v0
	v_pk_mul_f32 v[218:219], v[104:105], v[104:105]
	s_nop 0
	v_add_f32_e32 v218, v218, v219
	v_add_f32_e32 v0, v218, v0
	v_pk_mul_f32 v[218:219], v[84:85], v[84:85]
	s_nop 0
	v_add_f32_e32 v218, v218, v219
	v_add_f32_e32 v0, v218, v0
	v_pk_mul_f32 v[218:219], v[106:107], v[106:107]
	s_nop 0
	v_add_f32_e32 v218, v218, v219
	v_add_f32_e32 v0, v218, v0
	v_pk_mul_f32 v[218:219], v[86:87], v[86:87]
	s_nop 0
	v_add_f32_e32 v218, v218, v219
	v_add_f32_e32 v0, v218, v0
	v_pk_mul_f32 v[218:219], v[102:103], v[102:103]
	s_nop 0
	v_add_f32_e32 v218, v218, v219
	v_add_f32_e32 v0, v218, v0
	v_pk_mul_f32 v[218:219], v[76:77], v[76:77]
	s_nop 0
	v_add_f32_e32 v218, v218, v219
	v_add_f32_e32 v0, v218, v0
	v_pk_mul_f32 v[218:219], v[98:99], v[98:99]
	s_nop 0
	v_add_f32_e32 v218, v218, v219
	v_add_f32_e32 v0, v218, v0
	v_pk_mul_f32 v[218:219], v[82:83], v[82:83]
	s_nop 0
	v_add_f32_e32 v218, v218, v219
	v_add_f32_e32 v0, v218, v0
	v_pk_mul_f32 v[218:219], v[196:197], v[196:197]
	s_nop 0
	v_add_f32_e32 v218, v218, v219
	v_add_f32_e32 v0, v218, v0
	v_add_f32_e32 v0, v176, v0
	v_add_f32_e32 v0, v209, v0
	v_add_f32_e32 v0, v208, v0
	v_add_f32_e32 v0, v75, v0
	v_add_f32_e32 v0, v74, v0
	v_add_f32_e32 v0, v97, v0
	v_add_f32_e32 v0, v96, v0
	v_add_f32_e32 v0, v211, v0
	v_add_f32_e32 v0, v210, v0
	v_add_f32_e32 v0, v207, v0
	v_add_f32_e32 v0, v206, v0
	ds_bpermute_b32 v177, v231, v0
	global_load_dwordx4 v[218:221], v212, s[24:25] offset:640
	v_cvt_f64_f32_e32 v[74:75], v230
	v_mul_f64 v[96:97], v[74:75], s[84:85]
	v_rndne_f64_e32 v[96:97], v[96:97]
	s_waitcnt lgkmcnt(0)
	v_add_f32_e32 v0, v0, v177
	v_fmamk_f32 v0, v0, 0x3baaaaab, v232
	v_fma_f64 v[74:75], v[74:75], s[84:85], -v[96:97]
	v_mul_f32_e32 v96, 0x4b800000, v0
	v_cmp_gt_f32_e32 vcc, s5, v0
	v_sin_f32_e32 v177, v204
	v_sin_f32_e32 v176, v213
	v_cndmask_b32_e32 v0, v0, v96, vcc
	v_rsq_f32_e32 v0, v0
	s_nop 0
	v_mul_f32_e32 v96, 0x45800000, v0
	v_cndmask_b32_e32 v0, v0, v96, vcc
	v_mul_f32_e32 v0, 0x3dd53b94, v0
	v_pk_mul_f32 v[96:97], v[0:1], v[194:195] op_sel_hi:[0,1]
	v_pk_mul_f32 v[72:73], v[72:73], v[96:97]
	v_pk_mul_f32 v[96:97], v[0:1], v[202:203] op_sel_hi:[0,1]
	global_load_dwordx4 v[202:205], v212, s[24:25] offset:464
	global_load_dwordx4 v[206:209], v212, s[24:25] offset:448
	v_pk_mul_f32 v[70:71], v[70:71], v[96:97]
	global_load_dwordx4 v[210:213], v212, s[24:25] offset:400
	v_cvt_f64_f32_e32 v[96:97], v237
	v_cvt_f32_f64_e32 v194, v[74:75]
	v_pk_mul_f32 v[74:75], v[0:1], v[188:189] op_sel_hi:[0,1]
	v_mul_f64 v[188:189], v[96:97], s[84:85]
	v_rndne_f64_e32 v[188:189], v[188:189]
	v_pk_mul_f32 v[68:69], v[68:69], v[74:75]
	v_pk_mul_f32 v[74:75], v[0:1], v[198:199] op_sel_hi:[0,1]
	v_fma_f64 v[96:97], v[96:97], s[84:85], -v[188:189]
	v_pk_mul_f32 v[66:67], v[66:67], v[74:75]
	v_cvt_f32_f64_e32 v96, v[96:97]
	v_sin_f32_e32 v75, v96
	v_cos_f32_e32 v189, v96
	v_pk_mul_f32 v[96:97], v[142:143], v[66:67]
	v_pk_mul_f32 v[66:67], v[154:155], v[66:67]
	v_sin_f32_e32 v74, v194
	v_cos_f32_e32 v188, v194
	v_pk_fma_f32 v[194:195], v[154:155], v[70:71], v[96:97]
	v_pk_fma_f32 v[66:67], v[142:143], v[70:71], v[66:67] neg_lo:[0,0,1] neg_hi:[0,0,1]
	v_pk_mul_f32 v[70:71], v[0:1], v[190:191] op_sel_hi:[0,1]
	v_pk_mul_f32 v[60:61], v[60:61], v[70:71]
	v_pk_mul_f32 v[70:71], v[0:1], v[192:193] op_sel_hi:[0,1]
	v_pk_mul_f32 v[64:65], v[64:65], v[70:71]
	v_pk_mul_f32 v[76:77], v[0:1], v[76:77] op_sel_hi:[0,1]
	v_pk_mul_f32 v[70:71], v[152:153], v[64:65]
	v_pk_mul_f32 v[64:65], v[150:151], v[64:65]
	v_pk_fma_f32 v[70:71], v[150:151], v[60:61], v[70:71]
	v_pk_fma_f32 v[60:61], v[152:153], v[60:61], v[64:65] neg_lo:[0,0,1] neg_hi:[0,0,1]
	v_pk_mul_f32 v[64:65], v[0:1], v[196:197] op_sel_hi:[0,1]
	v_pk_mul_f32 v[58:59], v[58:59], v[64:65]
	v_pk_mul_f32 v[64:65], v[0:1], v[200:201] op_sel_hi:[0,1]
	v_pk_mul_f32 v[62:63], v[62:63], v[64:65]
	v_pk_mul_f32 v[56:57], v[56:57], v[76:77]
	v_pk_mul_f32 v[64:65], v[158:159], v[62:63]
	v_pk_mul_f32 v[62:63], v[160:161], v[62:63]
	v_pk_fma_f32 v[64:65], v[160:161], v[58:59], v[64:65]
	v_pk_fma_f32 v[58:59], v[158:159], v[58:59], v[62:63] neg_lo:[0,0,1] neg_hi:[0,0,1]
	v_pk_mul_f32 v[62:63], v[0:1], v[102:103] op_sel_hi:[0,1]
	v_pk_mul_f32 v[54:55], v[54:55], v[62:63]
	v_pk_mul_f32 v[62:63], v[0:1], v[178:179] op_sel_hi:[0,1]
	v_pk_mul_f32 v[76:77], v[0:1], v[78:79] op_sel_hi:[0,1]
	v_pk_mul_f32 v[80:81], v[0:1], v[80:81] op_sel_hi:[0,1]
	v_pk_mul_f32 v[100:101], v[0:1], v[100:101] op_sel_hi:[0,1]
	s_waitcnt vmcnt(0)
	v_pk_mul_f32 v[80:81], v[226:227], v[80:81]
	v_pk_mul_f32 v[82:83], v[0:1], v[82:83] op_sel_hi:[0,1]
	v_pk_mul_f32 v[142:143], v[228:229], v[100:101]
	v_pk_mul_f32 v[82:83], v[224:225], v[82:83]
	v_pk_mul_f32 v[100:101], v[188:189], v[142:143]
	s_waitcnt vmcnt(5)
	s_barrier
	v_pk_fma_f32 v[100:101], v[74:75], v[82:83], v[100:101]
	v_mov_b32_e32 v228, v238
	v_pk_mul_f32 v[62:63], v[218:219], v[62:63]
	v_pk_mul_f32 v[76:77], v[220:221], v[76:77]
	v_pk_mul_f32 v[96:97], v[122:123], v[62:63]
	v_pk_mul_f32 v[78:79], v[126:127], v[76:77]
	v_pk_fma_f32 v[96:97], v[124:125], v[54:55], v[96:97]
	v_pk_fma_f32 v[78:79], v[128:129], v[56:57], v[78:79]
	v_cvt_pk_bf16_f32 v96, v96, v97
	v_cvt_pk_bf16_f32 v97, v78, v79
	v_pk_mul_f32 v[78:79], v[0:1], v[98:99] op_sel_hi:[0,1]
	v_pk_mul_f32 v[78:79], v[222:223], v[78:79]
	v_pk_mul_f32 v[98:99], v[234:235], v[80:81]
	v_pk_mul_f32 v[62:63], v[124:125], v[62:63]
	v_pk_fma_f32 v[98:99], v[176:177], v[78:79], v[98:99]
	v_pk_fma_f32 v[54:55], v[122:123], v[54:55], v[62:63] neg_lo:[0,0,1] neg_hi:[0,0,1]
	v_cvt_pk_bf16_f32 v98, v98, v99
	v_cvt_pk_bf16_f32 v99, v100, v101
	v_cvt_pk_bf16_f32 v100, v54, v55
	v_pk_mul_f32 v[54:55], v[128:129], v[76:77]
	v_mov_b32_e32 v218, 0
	v_pk_fma_f32 v[54:55], v[126:127], v[56:57], v[54:55] neg_lo:[0,0,1] neg_hi:[0,0,1]
	s_nop 0
	v_cvt_pk_bf16_f32 v101, v54, v55
	v_pk_mul_f32 v[54:55], v[176:177], v[80:81]
	s_nop 0
	v_pk_fma_f32 v[54:55], v[234:235], v[78:79], v[54:55] neg_lo:[0,0,1] neg_hi:[0,0,1]
	s_nop 0
	v_cvt_pk_bf16_f32 v102, v54, v55
	v_pk_mul_f32 v[54:55], v[74:75], v[142:143]
	v_cvt_pk_bf16_f32 v142, v66, v67
	v_pk_fma_f32 v[54:55], v[188:189], v[82:83], v[54:55] neg_lo:[0,0,1] neg_hi:[0,0,1]
	s_nop 0
	v_cvt_pk_bf16_f32 v103, v54, v55
	v_pk_mul_f32 v[54:55], v[0:1], v[104:105] op_sel_hi:[0,1]
	v_pk_mul_f32 v[54:55], v[206:207], v[54:55]
	s_nop 0
	v_cvt_pk_bf16_f32 v104, v54, v55
	v_pk_mul_f32 v[54:55], v[0:1], v[84:85] op_sel_hi:[0,1]
	v_pk_mul_f32 v[54:55], v[208:209], v[54:55]
	s_nop 0
	v_cvt_pk_bf16_f32 v105, v54, v55
	v_pk_mul_f32 v[54:55], v[0:1], v[106:107] op_sel_hi:[0,1]
	v_pk_mul_f32 v[54:55], v[202:203], v[54:55]
	s_nop 0
	v_cvt_pk_bf16_f32 v106, v54, v55
	v_pk_mul_f32 v[54:55], v[0:1], v[86:87] op_sel_hi:[0,1]
	v_pk_mul_f32 v[54:55], v[204:205], v[54:55]
	s_nop 0
	v_cvt_pk_bf16_f32 v107, v54, v55
	v_pk_mul_f32 v[54:55], v[0:1], v[108:109] op_sel_hi:[0,1]
	v_pk_mul_f32 v[50:51], v[50:51], v[54:55]
	s_nop 0
	v_cvt_pk_bf16_f32 v108, v50, v51
	v_pk_mul_f32 v[50:51], v[0:1], v[88:89] op_sel_hi:[0,1]
	v_pk_mul_f32 v[50:51], v[52:53], v[50:51]
	s_nop 0
	v_cvt_pk_bf16_f32 v109, v50, v51
	v_pk_mul_f32 v[50:51], v[0:1], v[110:111] op_sel_hi:[0,1]
	v_pk_mul_f32 v[50:51], v[210:211], v[50:51]
	s_nop 0
	v_cvt_pk_bf16_f32 v110, v50, v51
	v_pk_mul_f32 v[50:51], v[0:1], v[90:91] op_sel_hi:[0,1]
	v_pk_mul_f32 v[50:51], v[212:213], v[50:51]
	s_nop 0
	v_cvt_pk_bf16_f32 v111, v50, v51
	v_pk_mul_f32 v[50:51], v[0:1], v[112:113] op_sel_hi:[0,1]
	v_pk_mul_f32 v[46:47], v[46:47], v[50:51]
	s_nop 0
	v_cvt_pk_bf16_f32 v112, v46, v47
	v_pk_mul_f32 v[46:47], v[0:1], v[92:93] op_sel_hi:[0,1]
	v_pk_mul_f32 v[46:47], v[48:49], v[46:47]
	s_nop 0
	v_cvt_pk_bf16_f32 v113, v46, v47
	v_pk_mul_f32 v[46:47], v[0:1], v[114:115] op_sel_hi:[0,1]
	v_pk_mul_f32 v[42:43], v[42:43], v[46:47]
	s_nop 0
	v_cvt_pk_bf16_f32 v114, v42, v43
	v_pk_mul_f32 v[42:43], v[0:1], v[94:95] op_sel_hi:[0,1]
	v_pk_mul_f32 v[42:43], v[44:45], v[42:43]
	s_nop 0
	v_cvt_pk_bf16_f32 v115, v42, v43
	v_pk_mul_f32 v[42:43], v[0:1], v[116:117] op_sel_hi:[0,1]
	v_pk_mul_f32 v[38:39], v[38:39], v[42:43]
	s_nop 0
	v_cvt_pk_bf16_f32 v116, v38, v39
	v_pk_mul_f32 v[38:39], v[0:1], v[186:187] op_sel_hi:[0,1]
	v_pk_mul_f32 v[38:39], v[40:41], v[38:39]
	s_nop 0
	v_cvt_pk_bf16_f32 v117, v38, v39
	v_pk_mul_f32 v[38:39], v[0:1], v[118:119] op_sel_hi:[0,1]
	v_pk_mul_f32 v[34:35], v[34:35], v[38:39]
	s_nop 0
	v_cvt_pk_bf16_f32 v118, v34, v35
	v_pk_mul_f32 v[34:35], v[0:1], v[184:185] op_sel_hi:[0,1]
	v_pk_mul_f32 v[34:35], v[36:37], v[34:35]
	s_nop 0
	v_cvt_pk_bf16_f32 v119, v34, v35
	v_pk_mul_f32 v[34:35], v[0:1], v[120:121] op_sel_hi:[0,1]
	v_pk_mul_f32 v[30:31], v[30:31], v[34:35]
	s_nop 0
	v_cvt_pk_bf16_f32 v120, v30, v31
	v_pk_mul_f32 v[30:31], v[0:1], v[174:175] op_sel_hi:[0,1]
	v_pk_mul_f32 v[30:31], v[32:33], v[30:31]
	s_nop 0
	v_cvt_pk_bf16_f32 v121, v30, v31
	v_pk_mul_f32 v[30:31], v[0:1], v[172:173] op_sel_hi:[0,1]
	v_pk_mul_f32 v[26:27], v[26:27], v[30:31]
	s_nop 0
	v_cvt_pk_bf16_f32 v122, v26, v27
	v_pk_mul_f32 v[26:27], v[0:1], v[170:171] op_sel_hi:[0,1]
	v_pk_mul_f32 v[26:27], v[28:29], v[26:27]
	s_nop 0
	v_cvt_pk_bf16_f32 v123, v26, v27
	v_pk_mul_f32 v[26:27], v[0:1], v[168:169] op_sel_hi:[0,1]
	v_pk_mul_f32 v[22:23], v[22:23], v[26:27]
	s_nop 0
	v_cvt_pk_bf16_f32 v124, v22, v23
	v_pk_mul_f32 v[22:23], v[0:1], v[166:167] op_sel_hi:[0,1]
	v_pk_mul_f32 v[22:23], v[24:25], v[22:23]
	s_nop 0
	v_cvt_pk_bf16_f32 v125, v22, v23
	v_pk_mul_f32 v[22:23], v[0:1], v[164:165] op_sel_hi:[0,1]
	v_pk_mul_f32 v[18:19], v[18:19], v[22:23]
	s_nop 0
	v_cvt_pk_bf16_f32 v126, v18, v19
	v_pk_mul_f32 v[18:19], v[0:1], v[162:163] op_sel_hi:[0,1]
	v_pk_mul_f32 v[18:19], v[20:21], v[18:19]
	s_nop 0
	v_cvt_pk_bf16_f32 v127, v18, v19
	v_pk_mul_f32 v[18:19], v[0:1], v[156:157] op_sel_hi:[0,1]
	v_pk_mul_f32 v[14:15], v[14:15], v[18:19]
	s_nop 0
	v_cvt_pk_bf16_f32 v128, v14, v15
	v_pk_mul_f32 v[14:15], v[0:1], v[148:149] op_sel_hi:[0,1]
	v_pk_mul_f32 v[14:15], v[16:17], v[14:15]
	s_nop 0
	v_cvt_pk_bf16_f32 v129, v14, v15
	v_pk_mul_f32 v[14:15], v[0:1], v[130:131] op_sel_hi:[0,1]
	v_pk_mul_f32 v[10:11], v[10:11], v[14:15]
	v_mov_b32_e32 v14, v1
	v_cvt_pk_bf16_f32 v130, v10, v11
	v_pk_mul_f32 v[10:11], v[0:1], v[140:141] op_sel_hi:[0,1]
	v_pk_mul_f32 v[10:11], v[12:13], v[10:11]
	v_mov_b32_e32 v15, v1
	v_cvt_pk_bf16_f32 v131, v10, v11
	v_pk_mul_f32 v[10:11], v[0:1], v[132:133] op_sel_hi:[0,1]
	v_pk_mul_f32 v[6:7], v[6:7], v[10:11]
	v_cvt_pk_bf16_f32 v140, v58, v59
	v_cvt_pk_bf16_f32 v132, v6, v7
	v_pk_mul_f32 v[6:7], v[0:1], v[138:139] op_sel_hi:[0,1]
	v_pk_mul_f32 v[6:7], v[8:9], v[6:7]
	v_cvt_pk_bf16_f32 v141, v60, v61
	v_cvt_pk_bf16_f32 v133, v6, v7
	v_pk_mul_f32 v[6:7], v[0:1], v[134:135] op_sel_hi:[0,1]
	v_pk_mul_f32 v[2:3], v[2:3], v[6:7]
	v_mov_b32_e32 v6, v1
	v_cvt_pk_bf16_f32 v134, v2, v3
	v_pk_mul_f32 v[2:3], v[0:1], v[136:137] op_sel_hi:[0,1]
	v_pk_mul_f32 v[2:3], v[4:5], v[2:3]
	v_cvt_pk_bf16_f32 v136, v64, v65
	v_cvt_pk_bf16_f32 v135, v2, v3
	v_pk_mul_f32 v[2:3], v[144:145], v[68:69]
	v_cvt_pk_bf16_f32 v137, v70, v71
	v_pk_fma_f32 v[2:3], v[146:147], v[72:73], v[2:3]
	v_mov_b32_e32 v0, v1
	v_cvt_pk_bf16_f32 v139, v2, v3
	v_pk_mul_f32 v[2:3], v[146:147], v[68:69]
	v_mov_b32_e32 v4, v1
	v_pk_fma_f32 v[2:3], v[144:145], v[72:73], v[2:3] neg_lo:[0,0,1] neg_hi:[0,0,1]
	v_mov_b32_e32 v5, v1
	v_cvt_pk_bf16_f32 v143, v2, v3
	v_mov_b32_e32 v2, v1
	v_mov_b32_e32 v3, v1
	v_mov_b32_e32 v7, v1
	v_mov_b32_e32 v8, v1
	v_mov_b32_e32 v9, v1
	v_mov_b32_e32 v10, v1
	v_mov_b32_e32 v11, v1
	v_mov_b32_e32 v12, v1
	v_mov_b32_e32 v13, v1
	v_mov_b64_e32 v[30:31], v[14:15]
	v_mov_b64_e32 v[46:47], v[14:15]
	v_mov_b64_e32 v[62:63], v[14:15]
	v_mov_b64_e32 v[78:79], v[14:15]
	v_cvt_pk_bf16_f32 v138, v194, v195
	v_mov_b64_e32 v[28:29], v[12:13]
	v_mov_b64_e32 v[26:27], v[10:11]
	v_mov_b64_e32 v[24:25], v[8:9]
	v_mov_b64_e32 v[22:23], v[6:7]
	v_mov_b64_e32 v[20:21], v[4:5]
	v_mov_b64_e32 v[18:19], v[2:3]
	v_mov_b64_e32 v[16:17], v[0:1]
	v_mov_b64_e32 v[44:45], v[12:13]
	v_mov_b64_e32 v[42:43], v[10:11]
	v_mov_b64_e32 v[40:41], v[8:9]
	v_mov_b64_e32 v[38:39], v[6:7]
	v_mov_b64_e32 v[36:37], v[4:5]
	v_mov_b64_e32 v[34:35], v[2:3]
	v_mov_b64_e32 v[32:33], v[0:1]
	v_mov_b64_e32 v[60:61], v[12:13]
	v_mov_b64_e32 v[58:59], v[10:11]
	v_mov_b64_e32 v[56:57], v[8:9]
	v_mov_b64_e32 v[54:55], v[6:7]
	v_mov_b64_e32 v[52:53], v[4:5]
	v_mov_b64_e32 v[50:51], v[2:3]
	v_mov_b64_e32 v[48:49], v[0:1]
	v_mov_b64_e32 v[76:77], v[12:13]
	v_mov_b64_e32 v[74:75], v[10:11]
	v_mov_b64_e32 v[72:73], v[8:9]
	v_mov_b64_e32 v[70:71], v[6:7]
	v_mov_b64_e32 v[68:69], v[4:5]
	v_mov_b64_e32 v[66:67], v[2:3]
	v_mov_b64_e32 v[64:65], v[0:1]
	v_mov_b32_e32 v206, v217
	v_lshlrev_b32_e32 v209, 3, v206
	v_lshrrev_b32_e32 v207, 1, v206
	v_lshlrev_b32_e32 v208, 7, v206
	v_and_b32_e32 v209, 8, v209
	v_ashrrev_i32_e32 v206, 5, v206
	v_add_u32_e32 v206, v209, v206
	v_and_b32_e32 v208, 0xf00, v208
	v_bitop3_b32 v209, v206, v207, 7 bitop3:0x78
	v_add_u32_e32 v210, 2, v206
	v_add_u32_e32 v211, 4, v206
	v_add_u32_e32 v206, 6, v206
	v_bitop3_b32 v210, v210, v207, 7 bitop3:0x78
	v_bitop3_b32 v211, v211, v207, 7 bitop3:0x78
	v_bitop3_b32 v206, v206, v207, 7 bitop3:0x78
	v_lshl_add_u32 v0, v209, 4, v208
	v_lshl_add_u32 v212, v210, 4, v208
	v_lshl_add_u32 v213, v211, 4, v208
	v_lshl_add_u32 v219, v206, 4, v208
	s_branch .LBB0_531

.LBB0_531:
	s_add_i32 s10, s33, 2
	s_cmp_ge_u32 s10, s28
	s_cselect_b64 s[22:23], -1, 0
	s_mov_b64 s[34:35], -1
	s_cmp_gt_i32 s33, s21
	s_cbranch_scc1 .Lat1_skip
	s_and_b64 vcc, exec, s[22:23]
	s_cbranch_vccnz .Lat1_nodma
	s_setprio 3
	s_mul_i32 s10, s0, 0xa000
	v_add_u32_e32 v14, s10, v0
	v_add_u32_e32 v15, s10, v212
	v_add_u32_e32 v176, s10, v213
	v_add_u32_e32 v177, s10, v219
	ds_read_b128 v[144:147], v14 offset:0
	ds_read_b128 v[148:151], v15 offset:0
	ds_read_b128 v[152:155], v176 offset:0
	ds_read_b128 v[156:159], v177 offset:0
	ds_read_b128 v[160:163], v14 offset:8192
	ds_read_b128 v[164:167], v15 offset:8192
	ds_read_b128 v[168:171], v176 offset:8192
	ds_read_b128 v[172:175], v177 offset:8192
	ds_read_b128 v[2:5], v14 offset:16384
	ds_read_b128 v[6:9], v15 offset:16384
	ds_read_b128 v[10:13], v176 offset:16384
	ds_read_b128 v[238:241], v177 offset:16384
	v_mad_u64_u32 v[202:203], s[10:11], s86, v228, v[180:181]
	s_mul_i32 s10, s7, 0xa000
	s_add_i32 s10, s9, s10
	s_mov_b32 m0, s10
	v_lshl_add_u64 v[204:205], v[202:203], 0, s[94:95]
	global_load_lds_dwordx4 v[202:203], off
	s_add_i32 m0, s10, 0x2000
	v_lshl_add_u64 v[202:203], v[202:203], 0, s[96:97]
	global_load_lds_dwordx4 v[204:205], off
	s_waitcnt lgkmcnt(8)
	v_mfma_f32_32x32x16_bf16 v[80:95], v[144:147], v[132:135], 0
	s_add_i32 m0, s10, 0x4000
	v_mfma_f32_32x32x16_bf16 v[80:95], v[148:151], v[128:131], v[80:95]
	global_load_lds_dwordx4 v[202:203], off
	v_lshl_add_u64 v[202:203], s[86:87], 1, v[182:183]
	s_add_i32 m0, s10, 0x6000
	v_mfma_f32_32x32x16_bf16 v[80:95], v[152:155], v[124:127], v[80:95]
	global_load_lds_dwordx4 v[202:203], off
	v_lshl_add_u64 v[202:203], v[202:203], 0, s[92:93]
	s_add_i32 m0, s10, 0x8000
	v_mfma_f32_32x32x16_bf16 v[80:95], v[156:159], v[120:123], v[80:95]
	global_load_lds_dwordx4 v[202:203], off
	ds_read_b128 v[144:147], v14 offset:4096
	ds_read_b128 v[148:151], v15 offset:4096
	ds_read_b128 v[152:155], v176 offset:4096
	ds_read_b128 v[156:159], v177 offset:4096
	s_waitcnt lgkmcnt(8)
	v_mfma_f32_32x32x16_bf16 v[80:95], v[160:163], v[116:119], v[80:95]
	v_mfma_f32_32x32x16_bf16 v[80:95], v[164:167], v[112:115], v[80:95]
	v_mfma_f32_32x32x16_bf16 v[80:95], v[168:171], v[108:111], v[80:95]
	v_mfma_f32_32x32x16_bf16 v[80:95], v[172:175], v[104:107], v[80:95]
	ds_read_b128 v[160:163], v14 offset:12288
	ds_read_b128 v[164:167], v15 offset:12288
	ds_read_b128 v[168:171], v176 offset:12288
	ds_read_b128 v[172:175], v177 offset:12288
	s_waitcnt lgkmcnt(8)
	v_mfma_f32_32x32x16_bf16 v[80:95], v[2:5], v[100:103], v[80:95]
	v_mfma_f32_32x32x16_bf16 v[80:95], v[6:9], v[140:143], v[80:95]
	v_mfma_f32_32x32x16_bf16 v[80:95], v[10:13], v[96:99], v[80:95]
	v_mfma_f32_32x32x16_bf16 v[80:95], v[238:241], v[136:139], v[80:95]
	s_setprio 2
	ds_read_b128 v[2:5], v14 offset:20480
	ds_read_b128 v[6:9], v15 offset:20480
	ds_read_b128 v[10:13], v176 offset:20480
	ds_read_b128 v[238:241], v177 offset:20480
	s_waitcnt lgkmcnt(8)
	v_mfma_f32_32x32x16_bf16 v[184:199], v[144:147], v[132:135], 0
	v_mfma_f32_32x32x16_bf16 v[184:199], v[148:151], v[128:131], v[184:199]
	v_mfma_f32_32x32x16_bf16 v[184:199], v[152:155], v[124:127], v[184:199]
	v_mfma_f32_32x32x16_bf16 v[184:199], v[156:159], v[120:123], v[184:199]
	ds_read_b128 v[144:147], v14 offset:24576
	ds_read_b128 v[148:151], v14 offset:28672
	ds_read_b128 v[152:155], v14 offset:32768
	ds_read_b128 v[156:159], v14 offset:36864
	s_waitcnt lgkmcnt(8)
	v_mfma_f32_32x32x16_bf16 v[184:199], v[160:163], v[116:119], v[184:199]
	v_med3_f32 v80, v80, s4, v236
	v_exp_f32_e32 v80, v80
	v_med3_f32 v81, v81, s4, v236
	v_exp_f32_e32 v81, v81
	v_mfma_f32_32x32x16_bf16 v[184:199], v[164:167], v[112:115], v[184:199]
	v_med3_f32 v82, v82, s4, v236
	v_exp_f32_e32 v82, v82
	v_med3_f32 v83, v83, s4, v236
	v_exp_f32_e32 v83, v83
	v_mfma_f32_32x32x16_bf16 v[184:199], v[168:171], v[108:111], v[184:199]
	v_med3_f32 v84, v84, s4, v236
	v_exp_f32_e32 v84, v84
	v_med3_f32 v85, v85, s4, v236
	v_exp_f32_e32 v85, v85
	v_mfma_f32_32x32x16_bf16 v[184:199], v[172:175], v[104:107], v[184:199]
	v_med3_f32 v86, v86, s4, v236
	v_exp_f32_e32 v86, v86
	v_med3_f32 v87, v87, s4, v236
	v_exp_f32_e32 v87, v87
	ds_read_b128 v[160:163], v15 offset:24576
	ds_read_b128 v[164:167], v15 offset:28672
	ds_read_b128 v[168:171], v15 offset:32768
	ds_read_b128 v[172:175], v15 offset:36864
	s_waitcnt lgkmcnt(8)
	v_mfma_f32_32x32x16_bf16 v[184:199], v[2:5], v[100:103], v[184:199]
	v_med3_f32 v88, v88, s4, v236
	v_exp_f32_e32 v88, v88
	v_med3_f32 v89, v89, s4, v236
	v_exp_f32_e32 v89, v89
	v_add_f32_e32 v200, v80, v81
	v_add_f32_e32 v200, v200, v82
	v_mfma_f32_32x32x16_bf16 v[184:199], v[6:9], v[140:143], v[184:199]
	v_med3_f32 v90, v90, s4, v236
	v_exp_f32_e32 v90, v90
	v_med3_f32 v91, v91, s4, v236
	v_exp_f32_e32 v91, v91
	v_add_f32_e32 v200, v200, v83
	v_add_f32_e32 v200, v200, v84
	v_mfma_f32_32x32x16_bf16 v[184:199], v[10:13], v[96:99], v[184:199]
	v_med3_f32 v92, v92, s4, v236
	v_exp_f32_e32 v92, v92
	v_med3_f32 v93, v93, s4, v236
	v_exp_f32_e32 v93, v93
	v_add_f32_e32 v200, v200, v85
	v_add_f32_e32 v200, v200, v86
	v_mfma_f32_32x32x16_bf16 v[184:199], v[238:241], v[136:139], v[184:199]
	v_med3_f32 v94, v94, s4, v236
	v_exp_f32_e32 v94, v94
	v_med3_f32 v95, v95, s4, v236
	v_exp_f32_e32 v95, v95
	v_add_f32_e32 v200, v200, v87
	s_setprio 1
	ds_read_b128 v[2:5], v176 offset:24576
	ds_read_b128 v[6:9], v176 offset:28672
	ds_read_b128 v[10:13], v176 offset:32768
	ds_read_b128 v[238:241], v176 offset:36864
	v_cvt_pk_bf16_f32 v80, v80, v81
	v_cvt_pk_bf16_f32 v81, v82, v83
	v_cvt_pk_bf16_f32 v82, v84, v85
	v_cvt_pk_bf16_f32 v83, v86, v87
	v_add_f32_e32 v200, v200, v88
	v_add_f32_e32 v200, v200, v89
	s_waitcnt lgkmcnt(8)
	v_mfma_f32_32x32x16_bf16 v[64:79], v[80:83], v[144:147], v[64:79]
	v_med3_f32 v184, v184, s4, v236
	v_exp_f32_e32 v184, v184
	v_med3_f32 v185, v185, s4, v236
	v_exp_f32_e32 v185, v185
	v_add_f32_e32 v200, v200, v90
	v_add_f32_e32 v200, v200, v91
	v_mfma_f32_32x32x16_bf16 v[48:63], v[80:83], v[148:151], v[48:63]
	v_med3_f32 v186, v186, s4, v236
	v_exp_f32_e32 v186, v186
	v_med3_f32 v187, v187, s4, v236
	v_exp_f32_e32 v187, v187
	v_add_f32_e32 v200, v200, v92
	v_add_f32_e32 v200, v200, v93
	v_mfma_f32_32x32x16_bf16 v[32:47], v[80:83], v[152:155], v[32:47]
	v_med3_f32 v188, v188, s4, v236
	v_exp_f32_e32 v188, v188
	v_med3_f32 v189, v189, s4, v236
	v_exp_f32_e32 v189, v189
	v_add_f32_e32 v200, v200, v94
	v_add_f32_e32 v200, v200, v95
	v_mfma_f32_32x32x16_bf16 v[16:31], v[80:83], v[156:159], v[16:31]
	v_med3_f32 v190, v190, s4, v236
	v_exp_f32_e32 v190, v190
	v_med3_f32 v191, v191, s4, v236
	v_exp_f32_e32 v191, v191
	v_cvt_pk_bf16_f32 v84, v88, v89
	v_cvt_pk_bf16_f32 v85, v90, v91
	v_cvt_pk_bf16_f32 v86, v92, v93
	v_cvt_pk_bf16_f32 v87, v94, v95
	ds_read_b128 v[144:147], v177 offset:24576
	ds_read_b128 v[148:151], v177 offset:28672
	ds_read_b128 v[152:155], v177 offset:32768
	ds_read_b128 v[156:159], v177 offset:36864
	s_waitcnt lgkmcnt(8)
	v_mfma_f32_32x32x16_bf16 v[64:79], v[84:87], v[160:163], v[64:79]
	v_med3_f32 v192, v192, s4, v236
	v_exp_f32_e32 v192, v192
	v_med3_f32 v193, v193, s4, v236
	v_exp_f32_e32 v193, v193
	v_add_f32_e32 v201, v184, v185
	v_add_f32_e32 v201, v201, v186
	v_mfma_f32_32x32x16_bf16 v[48:63], v[84:87], v[164:167], v[48:63]
	v_med3_f32 v194, v194, s4, v236
	v_exp_f32_e32 v194, v194
	v_med3_f32 v195, v195, s4, v236
	v_exp_f32_e32 v195, v195
	v_add_f32_e32 v201, v201, v187
	v_add_f32_e32 v201, v201, v188
	v_mfma_f32_32x32x16_bf16 v[32:47], v[84:87], v[168:171], v[32:47]
	v_med3_f32 v196, v196, s4, v236
	v_exp_f32_e32 v196, v196
	v_med3_f32 v197, v197, s4, v236
	v_exp_f32_e32 v197, v197
	v_add_f32_e32 v201, v201, v189
	v_mfma_f32_32x32x16_bf16 v[16:31], v[84:87], v[172:175], v[16:31]
	v_med3_f32 v198, v198, s4, v236
	v_exp_f32_e32 v198, v198
	v_med3_f32 v199, v199, s4, v236
	v_exp_f32_e32 v199, v199
	v_add_f32_e32 v201, v201, v190
	v_cvt_pk_bf16_f32 v184, v184, v185
	v_cvt_pk_bf16_f32 v185, v186, v187
	v_cvt_pk_bf16_f32 v186, v188, v189
	v_cvt_pk_bf16_f32 v187, v190, v191
	v_add_f32_e32 v201, v201, v191
	s_setprio 0
	s_waitcnt lgkmcnt(4)
	v_mfma_f32_32x32x16_bf16 v[64:79], v[184:187], v[2:5], v[64:79]
	v_add_f32_e32 v201, v201, v192
	v_add_f32_e32 v201, v201, v193
	v_add_f32_e32 v201, v201, v194
	v_mfma_f32_32x32x16_bf16 v[48:63], v[184:187], v[6:9], v[48:63]
	v_add_f32_e32 v201, v201, v195
	v_add_f32_e32 v201, v201, v196
	v_add_f32_e32 v201, v201, v197
	v_mfma_f32_32x32x16_bf16 v[32:47], v[184:187], v[10:13], v[32:47]
	v_add_f32_e32 v201, v201, v198
	v_add_f32_e32 v201, v201, v199
	v_cvt_pk_bf16_f32 v188, v192, v193
	v_cvt_pk_bf16_f32 v189, v194, v195
	v_cvt_pk_bf16_f32 v190, v196, v197
	v_cvt_pk_bf16_f32 v191, v198, v199
	v_mfma_f32_32x32x16_bf16 v[16:31], v[184:187], v[238:241], v[16:31]
	v_add_f32_e32 v200, v200, v201
	v_add_f32_e32 v218, v218, v200
	s_waitcnt lgkmcnt(0)
	v_mfma_f32_32x32x16_bf16 v[64:79], v[188:191], v[144:147], v[64:79]
	v_mfma_f32_32x32x16_bf16 v[48:63], v[188:191], v[148:151], v[48:63]
	v_mfma_f32_32x32x16_bf16 v[32:47], v[188:191], v[152:155], v[32:47]
	v_mfma_f32_32x32x16_bf16 v[16:31], v[188:191], v[156:159], v[16:31]
	s_waitcnt vmcnt(5) lgkmcnt(0)
	s_branch .LBB0_530
.Lat1_nodma:
	s_setprio 3
	s_mul_i32 s10, s0, 0xa000
	v_add_u32_e32 v14, s10, v0
	v_add_u32_e32 v15, s10, v212
	v_add_u32_e32 v176, s10, v213
	v_add_u32_e32 v177, s10, v219
	ds_read_b128 v[144:147], v14 offset:0
	ds_read_b128 v[148:151], v15 offset:0
	ds_read_b128 v[152:155], v176 offset:0
	ds_read_b128 v[156:159], v177 offset:0
	ds_read_b128 v[160:163], v14 offset:8192
	ds_read_b128 v[164:167], v15 offset:8192
	ds_read_b128 v[168:171], v176 offset:8192
	ds_read_b128 v[172:175], v177 offset:8192
	ds_read_b128 v[2:5], v14 offset:16384
	ds_read_b128 v[6:9], v15 offset:16384
	ds_read_b128 v[10:13], v176 offset:16384
	ds_read_b128 v[238:241], v177 offset:16384
	s_waitcnt lgkmcnt(8)
	v_mfma_f32_32x32x16_bf16 v[80:95], v[144:147], v[132:135], 0
	v_mfma_f32_32x32x16_bf16 v[80:95], v[148:151], v[128:131], v[80:95]
	v_mfma_f32_32x32x16_bf16 v[80:95], v[152:155], v[124:127], v[80:95]
	v_mfma_f32_32x32x16_bf16 v[80:95], v[156:159], v[120:123], v[80:95]
	ds_read_b128 v[144:147], v14 offset:4096
	ds_read_b128 v[148:151], v15 offset:4096
	ds_read_b128 v[152:155], v176 offset:4096
	ds_read_b128 v[156:159], v177 offset:4096
	s_waitcnt lgkmcnt(8)
	v_mfma_f32_32x32x16_bf16 v[80:95], v[160:163], v[116:119], v[80:95]
	v_mfma_f32_32x32x16_bf16 v[80:95], v[164:167], v[112:115], v[80:95]
	v_mfma_f32_32x32x16_bf16 v[80:95], v[168:171], v[108:111], v[80:95]
	v_mfma_f32_32x32x16_bf16 v[80:95], v[172:175], v[104:107], v[80:95]
	ds_read_b128 v[160:163], v14 offset:12288
	ds_read_b128 v[164:167], v15 offset:12288
	ds_read_b128 v[168:171], v176 offset:12288
	ds_read_b128 v[172:175], v177 offset:12288
	s_waitcnt lgkmcnt(8)
	v_mfma_f32_32x32x16_bf16 v[80:95], v[2:5], v[100:103], v[80:95]
	v_mfma_f32_32x32x16_bf16 v[80:95], v[6:9], v[140:143], v[80:95]
	v_mfma_f32_32x32x16_bf16 v[80:95], v[10:13], v[96:99], v[80:95]
	v_mfma_f32_32x32x16_bf16 v[80:95], v[238:241], v[136:139], v[80:95]
	s_setprio 2
	ds_read_b128 v[2:5], v14 offset:20480
	ds_read_b128 v[6:9], v15 offset:20480
	ds_read_b128 v[10:13], v176 offset:20480
	ds_read_b128 v[238:241], v177 offset:20480
	s_waitcnt lgkmcnt(8)
	v_mfma_f32_32x32x16_bf16 v[184:199], v[144:147], v[132:135], 0
	v_mfma_f32_32x32x16_bf16 v[184:199], v[148:151], v[128:131], v[184:199]
	v_mfma_f32_32x32x16_bf16 v[184:199], v[152:155], v[124:127], v[184:199]
	v_mfma_f32_32x32x16_bf16 v[184:199], v[156:159], v[120:123], v[184:199]
	ds_read_b128 v[144:147], v14 offset:24576
	ds_read_b128 v[148:151], v14 offset:28672
	ds_read_b128 v[152:155], v14 offset:32768
	ds_read_b128 v[156:159], v14 offset:36864
	s_waitcnt lgkmcnt(8)
	v_mfma_f32_32x32x16_bf16 v[184:199], v[160:163], v[116:119], v[184:199]
	v_med3_f32 v80, v80, s4, v236
	v_exp_f32_e32 v80, v80
	v_med3_f32 v81, v81, s4, v236
	v_exp_f32_e32 v81, v81
	v_mfma_f32_32x32x16_bf16 v[184:199], v[164:167], v[112:115], v[184:199]
	v_med3_f32 v82, v82, s4, v236
	v_exp_f32_e32 v82, v82
	v_med3_f32 v83, v83, s4, v236
	v_exp_f32_e32 v83, v83
	v_mfma_f32_32x32x16_bf16 v[184:199], v[168:171], v[108:111], v[184:199]
	v_med3_f32 v84, v84, s4, v236
	v_exp_f32_e32 v84, v84
	v_med3_f32 v85, v85, s4, v236
	v_exp_f32_e32 v85, v85
	v_mfma_f32_32x32x16_bf16 v[184:199], v[172:175], v[104:107], v[184:199]
	v_med3_f32 v86, v86, s4, v236
	v_exp_f32_e32 v86, v86
	v_med3_f32 v87, v87, s4, v236
	v_exp_f32_e32 v87, v87
	ds_read_b128 v[160:163], v15 offset:24576
	ds_read_b128 v[164:167], v15 offset:28672
	ds_read_b128 v[168:171], v15 offset:32768
	ds_read_b128 v[172:175], v15 offset:36864
	s_waitcnt lgkmcnt(8)
	v_mfma_f32_32x32x16_bf16 v[184:199], v[2:5], v[100:103], v[184:199]
	v_med3_f32 v88, v88, s4, v236
	v_exp_f32_e32 v88, v88
	v_med3_f32 v89, v89, s4, v236
	v_exp_f32_e32 v89, v89
	v_add_f32_e32 v200, v80, v81
	v_add_f32_e32 v200, v200, v82
	v_mfma_f32_32x32x16_bf16 v[184:199], v[6:9], v[140:143], v[184:199]
	v_med3_f32 v90, v90, s4, v236
	v_exp_f32_e32 v90, v90
	v_med3_f32 v91, v91, s4, v236
	v_exp_f32_e32 v91, v91
	v_add_f32_e32 v200, v200, v83
	v_add_f32_e32 v200, v200, v84
	v_mfma_f32_32x32x16_bf16 v[184:199], v[10:13], v[96:99], v[184:199]
	v_med3_f32 v92, v92, s4, v236
	v_exp_f32_e32 v92, v92
	v_med3_f32 v93, v93, s4, v236
	v_exp_f32_e32 v93, v93
	v_add_f32_e32 v200, v200, v85
	v_add_f32_e32 v200, v200, v86
	v_mfma_f32_32x32x16_bf16 v[184:199], v[238:241], v[136:139], v[184:199]
	v_med3_f32 v94, v94, s4, v236
	v_exp_f32_e32 v94, v94
	v_med3_f32 v95, v95, s4, v236
	v_exp_f32_e32 v95, v95
	v_add_f32_e32 v200, v200, v87
	s_setprio 1
	ds_read_b128 v[2:5], v176 offset:24576
	ds_read_b128 v[6:9], v176 offset:28672
	ds_read_b128 v[10:13], v176 offset:32768
	ds_read_b128 v[238:241], v176 offset:36864
	v_cvt_pk_bf16_f32 v80, v80, v81
	v_cvt_pk_bf16_f32 v81, v82, v83
	v_cvt_pk_bf16_f32 v82, v84, v85
	v_cvt_pk_bf16_f32 v83, v86, v87
	v_add_f32_e32 v200, v200, v88
	v_add_f32_e32 v200, v200, v89
	s_waitcnt lgkmcnt(8)
	v_mfma_f32_32x32x16_bf16 v[64:79], v[80:83], v[144:147], v[64:79]
	v_med3_f32 v184, v184, s4, v236
	v_exp_f32_e32 v184, v184
	v_med3_f32 v185, v185, s4, v236
	v_exp_f32_e32 v185, v185
	v_add_f32_e32 v200, v200, v90
	v_add_f32_e32 v200, v200, v91
	v_mfma_f32_32x32x16_bf16 v[48:63], v[80:83], v[148:151], v[48:63]
	v_med3_f32 v186, v186, s4, v236
	v_exp_f32_e32 v186, v186
	v_med3_f32 v187, v187, s4, v236
	v_exp_f32_e32 v187, v187
	v_add_f32_e32 v200, v200, v92
	v_add_f32_e32 v200, v200, v93
	v_mfma_f32_32x32x16_bf16 v[32:47], v[80:83], v[152:155], v[32:47]
	v_med3_f32 v188, v188, s4, v236
	v_exp_f32_e32 v188, v188
	v_med3_f32 v189, v189, s4, v236
	v_exp_f32_e32 v189, v189
	v_add_f32_e32 v200, v200, v94
	v_add_f32_e32 v200, v200, v95
	v_mfma_f32_32x32x16_bf16 v[16:31], v[80:83], v[156:159], v[16:31]
	v_med3_f32 v190, v190, s4, v236
	v_exp_f32_e32 v190, v190
	v_med3_f32 v191, v191, s4, v236
	v_exp_f32_e32 v191, v191
	v_cvt_pk_bf16_f32 v84, v88, v89
	v_cvt_pk_bf16_f32 v85, v90, v91
	v_cvt_pk_bf16_f32 v86, v92, v93
	v_cvt_pk_bf16_f32 v87, v94, v95
	ds_read_b128 v[144:147], v177 offset:24576
	ds_read_b128 v[148:151], v177 offset:28672
	ds_read_b128 v[152:155], v177 offset:32768
	ds_read_b128 v[156:159], v177 offset:36864
	s_waitcnt lgkmcnt(8)
	v_mfma_f32_32x32x16_bf16 v[64:79], v[84:87], v[160:163], v[64:79]
	v_med3_f32 v192, v192, s4, v236
	v_exp_f32_e32 v192, v192
	v_med3_f32 v193, v193, s4, v236
	v_exp_f32_e32 v193, v193
	v_add_f32_e32 v201, v184, v185
	v_add_f32_e32 v201, v201, v186
	v_mfma_f32_32x32x16_bf16 v[48:63], v[84:87], v[164:167], v[48:63]
	v_med3_f32 v194, v194, s4, v236
	v_exp_f32_e32 v194, v194
	v_med3_f32 v195, v195, s4, v236
	v_exp_f32_e32 v195, v195
	v_add_f32_e32 v201, v201, v187
	v_add_f32_e32 v201, v201, v188
	v_mfma_f32_32x32x16_bf16 v[32:47], v[84:87], v[168:171], v[32:47]
	v_med3_f32 v196, v196, s4, v236
	v_exp_f32_e32 v196, v196
	v_med3_f32 v197, v197, s4, v236
	v_exp_f32_e32 v197, v197
	v_add_f32_e32 v201, v201, v189
	v_mfma_f32_32x32x16_bf16 v[16:31], v[84:87], v[172:175], v[16:31]
	v_med3_f32 v198, v198, s4, v236
	v_exp_f32_e32 v198, v198
	v_med3_f32 v199, v199, s4, v236
	v_exp_f32_e32 v199, v199
	v_add_f32_e32 v201, v201, v190
	v_cvt_pk_bf16_f32 v184, v184, v185
	v_cvt_pk_bf16_f32 v185, v186, v187
	v_cvt_pk_bf16_f32 v186, v188, v189
	v_cvt_pk_bf16_f32 v187, v190, v191
	v_add_f32_e32 v201, v201, v191
	s_setprio 0
	s_waitcnt lgkmcnt(4)
	v_mfma_f32_32x32x16_bf16 v[64:79], v[184:187], v[2:5], v[64:79]
	v_add_f32_e32 v201, v201, v192
	v_add_f32_e32 v201, v201, v193
	v_add_f32_e32 v201, v201, v194
	v_mfma_f32_32x32x16_bf16 v[48:63], v[184:187], v[6:9], v[48:63]
	v_add_f32_e32 v201, v201, v195
	v_add_f32_e32 v201, v201, v196
	v_add_f32_e32 v201, v201, v197
	v_mfma_f32_32x32x16_bf16 v[32:47], v[184:187], v[10:13], v[32:47]
	v_add_f32_e32 v201, v201, v198
	v_add_f32_e32 v201, v201, v199
	v_cvt_pk_bf16_f32 v188, v192, v193
	v_cvt_pk_bf16_f32 v189, v194, v195
	v_cvt_pk_bf16_f32 v190, v196, v197
	v_cvt_pk_bf16_f32 v191, v198, v199
	v_mfma_f32_32x32x16_bf16 v[16:31], v[184:187], v[238:241], v[16:31]
	v_add_f32_e32 v200, v200, v201
	v_add_f32_e32 v218, v218, v200
	s_waitcnt lgkmcnt(0)
	v_mfma_f32_32x32x16_bf16 v[64:79], v[188:191], v[144:147], v[64:79]
	v_mfma_f32_32x32x16_bf16 v[48:63], v[188:191], v[148:151], v[48:63]
	v_mfma_f32_32x32x16_bf16 v[32:47], v[188:191], v[152:155], v[32:47]
	v_mfma_f32_32x32x16_bf16 v[16:31], v[188:191], v[156:159], v[16:31]
	s_waitcnt vmcnt(0) lgkmcnt(0)
	s_branch .LBB0_530

.LBB0_571:
	s_or_b64 exec, exec, s[8:9]
	v_mov_b32_e32 v0, v1
	s_waitcnt vmcnt(0) lgkmcnt(0)
	s_barrier
	s_lshl_b32 s8, s43, 8
	v_mbcnt_lo_u32_b32 v0, -1, v0
	v_mbcnt_hi_u32_b32 v0, -1, v0
	v_add_u32_e32 v98, s54, v0
	v_mov_b64_e32 v[2:3], s[70:71]
	v_readfirstlane_b32 s9, v98
	s_ashr_i32 s0, s9, 6
	s_lshl_b32 s6, s0, 5
	v_and_b32_e32 v238, 31, v98
	s_add_i32 s20, s6, s8
	v_or_b32_e32 v34, s20, v238
	v_bfe_u32 v237, v98, 5, 1
	v_mad_i64_i32 v[2:3], s[10:11], v34, s46, v[2:3]
	s_lshl_b32 s86, s45, 1
	v_lshl_add_u64 v[2:3], v[2:3], 0, s[86:87]
	v_lshlrev_b32_e32 v0, 4, v237
	v_lshl_add_u64 v[2:3], v[2:3], 0, v[0:1]
	global_load_dwordx4 v[38:41], v[2:3], off
	global_load_dwordx4 v[46:49], v[2:3], off offset:32
	global_load_dwordx4 v[54:57], v[2:3], off offset:64
	global_load_dwordx4 v[62:65], v[2:3], off offset:96
	global_load_dwordx4 v[30:33], v[2:3], off offset:128
	global_load_dwordx4 v[26:29], v[2:3], off offset:160
	global_load_dwordx4 v[22:25], v[2:3], off offset:192
	global_load_dwordx4 v[18:21], v[2:3], off offset:224
	global_load_dwordx4 v[14:17], v[2:3], off offset:256
	global_load_dwordx4 v[6:9], v[2:3], off offset:288
	global_load_dwordx4 v[10:13], v[2:3], off offset:320
	s_nop 0
	global_load_dwordx4 v[2:5], v[2:3], off offset:352
	v_ashrrev_i32_e32 v35, 31, v34
	v_lshl_add_u64 v[34:35], v[34:35], 2, s[68:69]
	global_load_dword v239, v[34:35], off
	s_lshl_b32 s7, s0, 2
	v_bfe_u32 v102, v98, 3, 1
	v_mov_b64_e32 v[100:101], s[66:67]
	s_lshl_b32 s0, s0, 10
	s_add_i32 s0, s0, 0
	s_mov_b32 m0, s0
	s_waitcnt vmcnt(12)
	v_lshlrev_b32_e32 v118, 16, v38
	v_and_b32_e32 v119, 0xffff0000, v38
	v_lshlrev_b32_e32 v120, 16, v39
	v_and_b32_e32 v121, 0xffff0000, v39
	v_pk_mul_f32 v[34:35], v[118:119], v[118:119]
	v_pk_mul_f32 v[36:37], v[120:121], v[120:121]
	v_lshlrev_b32_e32 v122, 16, v40
	v_and_b32_e32 v123, 0xffff0000, v40
	v_pk_mul_f32 v[38:39], v[122:123], v[122:123]
	v_lshlrev_b32_e32 v124, 16, v41
	v_and_b32_e32 v125, 0xffff0000, v41
	v_add_f32_e32 v36, v36, v37
	v_add_f32_e32 v34, v34, v35
	v_pk_mul_f32 v[40:41], v[124:125], v[124:125]
	s_waitcnt vmcnt(11)
	v_lshlrev_b32_e32 v114, 16, v46
	v_and_b32_e32 v115, 0xffff0000, v46
	v_add_f32_e32 v34, v34, v36
	v_add_f32_e32 v35, v38, v39
	v_pk_mul_f32 v[42:43], v[114:115], v[114:115]
	v_lshlrev_b32_e32 v116, 16, v47
	v_and_b32_e32 v117, 0xffff0000, v47
	v_add_f32_e32 v0, v40, v41
	v_add_f32_e32 v34, v35, v34
	v_pk_mul_f32 v[44:45], v[116:117], v[116:117]
	v_lshlrev_b32_e32 v126, 16, v48
	v_and_b32_e32 v127, 0xffff0000, v48
	v_add_f32_e32 v0, v0, v34
	v_add_f32_e32 v34, v42, v43
	v_pk_mul_f32 v[46:47], v[126:127], v[126:127]
	v_lshlrev_b32_e32 v128, 16, v49
	v_and_b32_e32 v129, 0xffff0000, v49
	v_add_f32_e32 v0, v34, v0
	v_add_f32_e32 v34, v44, v45
	v_pk_mul_f32 v[48:49], v[128:129], v[128:129]
	s_waitcnt vmcnt(10)
	v_lshlrev_b32_e32 v130, 16, v54
	v_and_b32_e32 v131, 0xffff0000, v54
	v_add_f32_e32 v0, v34, v0
	v_add_f32_e32 v34, v46, v47
	v_pk_mul_f32 v[50:51], v[130:131], v[130:131]
	v_lshlrev_b32_e32 v132, 16, v55
	v_and_b32_e32 v133, 0xffff0000, v55
	v_add_f32_e32 v0, v34, v0
	v_add_f32_e32 v34, v48, v49
	v_pk_mul_f32 v[52:53], v[132:133], v[132:133]
	v_lshlrev_b32_e32 v134, 16, v56
	v_and_b32_e32 v135, 0xffff0000, v56
	v_add_f32_e32 v0, v34, v0
	v_add_f32_e32 v34, v50, v51
	v_pk_mul_f32 v[54:55], v[134:135], v[134:135]
	v_lshlrev_b32_e32 v136, 16, v57
	v_and_b32_e32 v137, 0xffff0000, v57
	v_add_f32_e32 v0, v34, v0
	v_add_f32_e32 v34, v52, v53
	v_pk_mul_f32 v[56:57], v[136:137], v[136:137]
	s_waitcnt vmcnt(9)
	v_lshlrev_b32_e32 v138, 16, v62
	v_and_b32_e32 v139, 0xffff0000, v62
	v_add_f32_e32 v0, v34, v0
	v_add_f32_e32 v34, v54, v55
	v_pk_mul_f32 v[58:59], v[138:139], v[138:139]
	v_lshlrev_b32_e32 v140, 16, v63
	v_and_b32_e32 v141, 0xffff0000, v63
	v_add_f32_e32 v0, v34, v0
	v_add_f32_e32 v34, v56, v57
	v_pk_mul_f32 v[60:61], v[140:141], v[140:141]
	v_lshlrev_b32_e32 v142, 16, v64
	v_and_b32_e32 v143, 0xffff0000, v64
	v_add_f32_e32 v0, v34, v0
	v_add_f32_e32 v34, v58, v59
	v_pk_mul_f32 v[62:63], v[142:143], v[142:143]
	v_lshlrev_b32_e32 v144, 16, v65
	v_and_b32_e32 v145, 0xffff0000, v65
	v_add_f32_e32 v0, v34, v0
	v_add_f32_e32 v34, v60, v61
	v_pk_mul_f32 v[64:65], v[144:145], v[144:145]
	s_waitcnt vmcnt(8)
	v_lshlrev_b32_e32 v146, 16, v30
	v_and_b32_e32 v147, 0xffff0000, v30
	v_add_f32_e32 v0, v34, v0
	v_add_f32_e32 v34, v62, v63
	v_pk_mul_f32 v[66:67], v[146:147], v[146:147]
	v_lshlrev_b32_e32 v148, 16, v31
	v_and_b32_e32 v149, 0xffff0000, v31
	v_add_f32_e32 v0, v34, v0
	v_add_f32_e32 v34, v64, v65
	v_pk_mul_f32 v[30:31], v[148:149], v[148:149]
	v_lshlrev_b32_e32 v150, 16, v32
	v_and_b32_e32 v151, 0xffff0000, v32
	v_add_f32_e32 v0, v34, v0
	v_add_f32_e32 v34, v66, v67
	v_pk_mul_f32 v[68:69], v[150:151], v[150:151]
	v_lshlrev_b32_e32 v152, 16, v33
	v_and_b32_e32 v153, 0xffff0000, v33
	v_add_f32_e32 v0, v34, v0
	v_add_f32_e32 v30, v30, v31
	v_pk_mul_f32 v[32:33], v[152:153], v[152:153]
	s_waitcnt vmcnt(7)
	v_lshlrev_b32_e32 v154, 16, v26
	v_and_b32_e32 v155, 0xffff0000, v26
	v_add_f32_e32 v0, v30, v0
	v_add_f32_e32 v30, v68, v69
	v_pk_mul_f32 v[70:71], v[154:155], v[154:155]
	v_lshlrev_b32_e32 v160, 16, v27
	v_and_b32_e32 v161, 0xffff0000, v27
	v_add_f32_e32 v0, v30, v0
	v_add_f32_e32 v30, v32, v33
	v_pk_mul_f32 v[26:27], v[160:161], v[160:161]
	v_lshlrev_b32_e32 v158, 16, v28
	v_and_b32_e32 v159, 0xffff0000, v28
	v_add_f32_e32 v0, v30, v0
	v_add_f32_e32 v30, v70, v71
	v_pk_mul_f32 v[72:73], v[158:159], v[158:159]
	v_lshlrev_b32_e32 v156, 16, v29
	v_and_b32_e32 v157, 0xffff0000, v29
	v_add_f32_e32 v0, v30, v0
	v_add_f32_e32 v26, v26, v27
	v_pk_mul_f32 v[28:29], v[156:157], v[156:157]
	s_waitcnt vmcnt(6)
	v_lshlrev_b32_e32 v162, 16, v22
	v_and_b32_e32 v163, 0xffff0000, v22
	v_add_f32_e32 v0, v26, v0
	v_add_f32_e32 v26, v72, v73
	v_pk_mul_f32 v[74:75], v[162:163], v[162:163]
	v_lshlrev_b32_e32 v166, 16, v23
	v_and_b32_e32 v167, 0xffff0000, v23
	v_add_f32_e32 v0, v26, v0
	v_add_f32_e32 v26, v28, v29
	v_pk_mul_f32 v[22:23], v[166:167], v[166:167]
	v_lshlrev_b32_e32 v164, 16, v24
	v_and_b32_e32 v165, 0xffff0000, v24
	v_add_f32_e32 v0, v26, v0
	v_add_f32_e32 v26, v74, v75
	v_pk_mul_f32 v[76:77], v[164:165], v[164:165]
	v_lshlrev_b32_e32 v168, 16, v25
	v_and_b32_e32 v169, 0xffff0000, v25
	v_add_f32_e32 v0, v26, v0
	v_add_f32_e32 v22, v22, v23
	v_pk_mul_f32 v[24:25], v[168:169], v[168:169]
	s_waitcnt vmcnt(5)
	v_lshlrev_b32_e32 v170, 16, v18
	v_and_b32_e32 v171, 0xffff0000, v18
	v_add_f32_e32 v0, v22, v0
	v_add_f32_e32 v22, v76, v77
	v_pk_mul_f32 v[78:79], v[170:171], v[170:171]
	v_lshlrev_b32_e32 v172, 16, v19
	v_and_b32_e32 v173, 0xffff0000, v19
	v_add_f32_e32 v0, v22, v0
	v_add_f32_e32 v22, v24, v25
	v_pk_mul_f32 v[18:19], v[172:173], v[172:173]
	v_lshlrev_b32_e32 v182, 16, v20
	v_and_b32_e32 v183, 0xffff0000, v20
	v_add_f32_e32 v0, v22, v0
	v_add_f32_e32 v22, v78, v79
	v_pk_mul_f32 v[80:81], v[182:183], v[182:183]
	v_lshlrev_b32_e32 v184, 16, v21
	v_and_b32_e32 v185, 0xffff0000, v21
	v_add_f32_e32 v0, v22, v0
	v_add_f32_e32 v18, v18, v19
	v_pk_mul_f32 v[20:21], v[184:185], v[184:185]
	s_waitcnt vmcnt(4)
	v_lshlrev_b32_e32 v188, 16, v14
	v_and_b32_e32 v189, 0xffff0000, v14
	v_add_f32_e32 v0, v18, v0
	v_add_f32_e32 v18, v80, v81
	v_pk_mul_f32 v[82:83], v[188:189], v[188:189]
	v_lshlrev_b32_e32 v186, 16, v15
	v_and_b32_e32 v187, 0xffff0000, v15
	v_add_f32_e32 v0, v18, v0
	v_add_f32_e32 v18, v20, v21
	v_pk_mul_f32 v[14:15], v[186:187], v[186:187]
	v_lshlrev_b32_e32 v196, 16, v16
	v_and_b32_e32 v197, 0xffff0000, v16
	v_add_f32_e32 v0, v18, v0
	v_add_f32_e32 v18, v82, v83
	v_pk_mul_f32 v[84:85], v[196:197], v[196:197]
	v_lshlrev_b32_e32 v194, 16, v17
	v_and_b32_e32 v195, 0xffff0000, v17
	v_add_f32_e32 v0, v18, v0
	v_add_f32_e32 v14, v14, v15
	v_pk_mul_f32 v[16:17], v[194:195], v[194:195]
	s_waitcnt vmcnt(3)
	v_lshlrev_b32_e32 v202, 16, v6
	v_and_b32_e32 v203, 0xffff0000, v6
	v_add_f32_e32 v0, v14, v0
	v_add_f32_e32 v14, v84, v85
	s_waitcnt vmcnt(2)
	v_and_b32_e32 v193, 0xffff0000, v11
	v_pk_mul_f32 v[86:87], v[202:203], v[202:203]
	v_lshlrev_b32_e32 v206, 16, v7
	v_and_b32_e32 v207, 0xffff0000, v7
	v_and_b32_e32 v201, 0xffff0000, v9
	v_add_f32_e32 v0, v14, v0
	v_add_f32_e32 v14, v16, v17
	v_lshlrev_b32_e32 v192, 16, v10
	v_and_b32_e32 v215, 0xffff0000, v10
	v_mov_b32_e32 v214, v193
	v_pk_mul_f32 v[6:7], v[206:207], v[206:207]
	v_lshlrev_b32_e32 v212, 16, v8
	v_and_b32_e32 v223, 0xffff0000, v8
	v_mov_b32_e32 v222, v201
	v_add_f32_e32 v0, v14, v0
	v_add_f32_e32 v14, v86, v87
	v_lshlrev_b32_e32 v190, 16, v11
	v_mov_b32_e32 v191, v192
	v_pk_mul_f32 v[10:11], v[214:215], v[214:215]
	v_lshlrev_b32_e32 v220, 16, v9
	v_mov_b32_e32 v221, v212
	v_pk_mul_f32 v[8:9], v[222:223], v[222:223]
	v_add_f32_e32 v0, v14, v0
	v_add_f32_e32 v6, v6, v7
	v_pk_fma_f32 v[10:11], v[190:191], v[190:191], v[10:11]
	v_and_b32_e32 v191, 0xffff0000, v13
	v_pk_fma_f32 v[8:9], v[220:221], v[220:221], v[8:9]
	v_add_f32_e32 v0, v6, v0
	v_lshlrev_b32_e32 v200, 16, v12
	v_and_b32_e32 v217, 0xffff0000, v12
	v_mov_b32_e32 v216, v191
	v_add_f32_e32 v0, v9, v0
	v_lshlrev_b32_e32 v198, 16, v13
	v_mov_b32_e32 v199, v200
	v_pk_mul_f32 v[12:13], v[216:217], v[216:217]
	v_add_f32_e32 v0, v8, v0
	v_pk_fma_f32 v[12:13], v[198:199], v[198:199], v[12:13]
	s_waitcnt vmcnt(1)
	v_and_b32_e32 v199, 0xffff0000, v3
	v_add_f32_e32 v0, v11, v0
	v_lshlrev_b32_e32 v204, 16, v2
	v_and_b32_e32 v219, 0xffff0000, v2
	v_mov_b32_e32 v218, v199
	v_add_f32_e32 v0, v10, v0
	v_lshlrev_b32_e32 v208, 16, v3
	v_mov_b32_e32 v209, v204
	v_pk_mul_f32 v[2:3], v[218:219], v[218:219]
	v_and_b32_e32 v205, 0xffff0000, v5
	v_add_f32_e32 v0, v13, v0
	v_pk_fma_f32 v[2:3], v[208:209], v[208:209], v[2:3]
	v_lshlrev_b32_e32 v210, 16, v4
	v_and_b32_e32 v225, 0xffff0000, v4
	v_mov_b32_e32 v224, v205
	v_add_f32_e32 v0, v12, v0
	v_lshlrev_b32_e32 v226, 16, v5
	v_mov_b32_e32 v227, v210
	v_pk_mul_f32 v[4:5], v[224:225], v[224:225]
	v_add_f32_e32 v0, v3, v0
	v_pk_fma_f32 v[4:5], v[226:227], v[226:227], v[4:5]
	v_add_f32_e32 v0, v2, v0
	v_add_f32_e32 v0, v5, v0
	v_add_f32_e32 v209, v4, v0
	v_and_b32_e32 v0, 32, v98
	global_load_dwordx4 v[2:5], v0, s[24:25] offset:16
	global_load_dwordx4 v[14:17], v0, s[24:25]
	global_load_dwordx4 v[18:21], v0, s[24:25] offset:80
	global_load_dwordx4 v[22:25], v0, s[24:25] offset:64
	global_load_dwordx4 v[26:29], v0, s[24:25] offset:144
	global_load_dwordx4 v[30:33], v0, s[24:25] offset:128
	global_load_dwordx4 v[34:37], v0, s[24:25] offset:208
	global_load_dwordx4 v[38:41], v0, s[24:25] offset:192
	global_load_dwordx4 v[42:45], v0, s[24:25] offset:272
	global_load_dwordx4 v[46:49], v0, s[24:25] offset:256
	global_load_dwordx4 v[50:53], v0, s[24:25] offset:336
	global_load_dwordx4 v[54:57], v0, s[24:25] offset:320
	global_load_dwordx4 v[58:61], v0, s[24:25] offset:400
	global_load_dwordx4 v[62:65], v0, s[24:25] offset:384
	global_load_dwordx4 v[66:69], v0, s[24:25] offset:464
	global_load_dwordx4 v[70:73], v0, s[24:25] offset:448
	global_load_dwordx4 v[78:81], v0, s[24:25] offset:528
	global_load_dwordx4 v[86:89], v0, s[24:25] offset:512
	global_load_dwordx4 v[74:77], v0, s[24:25] offset:656
	global_load_dwordx4 v[82:85], v0, s[24:25] offset:640
	global_load_dwordx4 v[10:13], v0, s[24:25] offset:592
	global_load_dwordx4 v[90:93], v0, s[24:25] offset:576
	global_load_dwordx4 v[6:9], v0, s[24:25] offset:720
	global_load_dwordx4 v[94:97], v0, s[24:25] offset:704
	v_bfe_u32 v0, v98, 4, 2
	v_or_b32_e32 v99, s7, v0
	v_lshlrev_b32_e32 v99, 1, v99
	v_bitop3_b32 v0, s7, v98, v0 bitop3:0x36
	v_or_b32_e32 v103, v99, v102
	v_mad_i64_i32 v[100:101], s[10:11], v103, s46, v[100:101]
	v_lshlrev_b32_e32 v0, 4, v0
	v_lshl_add_u64 v[100:101], v[100:101], 0, s[86:87]
	v_and_b32_e32 v0, 0x70, v0
	v_add_u32_e32 v99, s44, v99
	v_lshl_add_u64 v[174:175], v[100:101], 0, v[0:1]
	v_or_b32_e32 v100, v99, v102
	v_ashrrev_i32_e32 v101, 31, v100
	v_lshlrev_b64 v[100:101], 15, v[100:101]
	global_load_lds_dwordx4 v[174:175], off
	v_lshl_add_u64 v[102:103], v[174:175], 0, s[94:95]
	s_add_i32 m0, s0, 0x2000
	v_lshl_add_u64 v[100:101], s[12:13], 0, v[100:101]
	global_load_lds_dwordx4 v[102:103], off
	v_lshl_add_u64 v[102:103], v[174:175], 0, s[96:97]
	s_add_i32 m0, s0, 0x4000
	v_lshl_add_u64 v[180:181], v[100:101], 0, v[0:1]
	global_load_lds_dwordx4 v[102:103], off
	s_add_i32 m0, s0, 0x6000
	v_lshl_add_u64 v[100:101], v[180:181], 0, s[92:93]
	global_load_lds_dwordx4 v[180:181], off
	s_add_i32 m0, s0, 0x8000
	s_mov_b64 s[10:11], 0x30000
	global_load_lds_dwordx4 v[100:101], off
	v_lshl_add_u64 v[100:101], v[174:175], 0, s[10:11]
	s_add_i32 m0, s0, 0xa000
	s_mov_b64 s[10:11], 0x30080
	global_load_lds_dwordx4 v[100:101], off
	v_lshl_add_u64 v[100:101], v[174:175], 0, s[10:11]
	s_add_i32 m0, s0, 0xc000
	s_mov_b64 s[10:11], 0x30100
	global_load_lds_dwordx4 v[100:101], off
	v_lshl_add_u64 v[100:101], v[174:175], 0, s[10:11]
	s_add_i32 m0, s0, 0xe000
	s_mov_b64 s[10:11], 0x200080
	global_load_lds_dwordx4 v[100:101], off
	s_add_i32 m0, s0, 0x10000
	v_lshl_add_u64 v[100:101], v[180:181], 0, s[94:95]
	global_load_lds_dwordx4 v[100:101], off
	v_lshl_add_u64 v[100:101], v[180:181], 0, s[10:11]
	s_add_i32 m0, s0, 0x12000
	ds_bpermute_b32 v211, v231, v209
	global_load_lds_dwordx4 v[100:101], off
	s_waitcnt vmcnt(5)
	s_barrier
	s_cmp_lt_i32 s43, 0
	s_cbranch_scc1 .LBB0_582
	v_lshlrev_b32_e32 v0, 3, v237
	v_lshlrev_b32_e32 v0, 2, v0
	v_and_b32_e32 v222, 63, v98
	global_load_dwordx4 v[98:101], v0, s[26:27] offset:192
	global_load_dwordx4 v[102:105], v0, s[26:27] offset:176
	global_load_dwordx4 v[106:109], v0, s[26:27] offset:240
	global_load_dwordx4 v[110:113], v0, s[26:27] offset:256
	s_waitcnt lgkmcnt(0)
	v_add_f32_e32 v0, v209, v211
	v_fmamk_f32 v0, v0, 0x3baaaaab, v232
	v_cmp_gt_f32_e32 vcc, s5, v0
	v_mul_f32_e32 v176, 0x4b800000, v0
	v_mov_b32_e32 v213, v223
	v_cndmask_b32_e32 v0, v0, v176, vcc
	v_rsq_f32_e32 v0, v0
	s_waitcnt vmcnt(0)
	v_cvt_f32_i32_e32 v223, v239
	v_mov_b32_e32 v221, v201
	v_mov_b32_e32 v227, v205
	v_mul_f32_e32 v176, 0x45800000, v0
	v_cndmask_b32_e32 v0, v0, v176, vcc
	v_mul_f32_e32 v0, 0x3dd53b94, v0
	v_mov_b32_e32 v205, v219
	v_mov_b32_e32 v201, v217
	v_pk_mul_f32 v[216:217], v[0:1], v[220:221] op_sel_hi:[0,1]
	v_mov_b32_e32 v211, v225
	v_mov_b32_e32 v209, v199
	v_mov_b32_e32 v199, v191
	v_mov_b32_e32 v191, v193
	v_mov_b32_e32 v193, v215
	v_pk_mul_f32 v[214:215], v[0:1], v[226:227] op_sel_hi:[0,1]
	s_lshl_b32 s21, s43, 2
	s_ashr_i32 s9, s9, 7
	s_mov_b32 s7, 2
	s_add_i32 s9, s9, s21
	s_add_i32 s21, s21, 4
	s_mov_b32 s28, 0
	s_movk_i32 s86, 0x80
	s_mov_b32 s33, 0
	v_mul_f32_e32 v99, v99, v223
	v_mul_f32_e32 v98, v98, v223
	v_mul_f32_e32 v109, v109, v223
	v_mul_f32_e32 v113, v113, v223
	v_cvt_f64_f32_e32 v[176:177], v113
	v_mul_f64 v[178:179], v[176:177], s[84:85]
	v_rndne_f64_e32 v[178:179], v[178:179]
	v_fma_f64 v[176:177], v[176:177], s[84:85], -v[178:179]
	v_cvt_f32_f64_e32 v113, v[176:177]
	v_mul_f32_e32 v112, v112, v223
	v_cos_f32_e32 v219, v113
	v_sin_f32_e32 v221, v113
	v_cvt_f64_f32_e32 v[112:113], v112
	v_mul_f64 v[176:177], v[112:113], s[84:85]
	v_rndne_f64_e32 v[176:177], v[176:177]
	v_fma_f64 v[112:113], v[112:113], s[84:85], -v[176:177]
	v_cvt_f32_f64_e32 v112, v[112:113]
	v_mul_f32_e32 v111, v111, v223
	v_sin_f32_e32 v220, v112
	v_cos_f32_e32 v218, v112
	v_cvt_f64_f32_e32 v[112:113], v111
	v_mul_f64 v[176:177], v[112:113], s[84:85]
	v_rndne_f64_e32 v[176:177], v[176:177]
	v_mul_f32_e32 v110, v110, v223
	v_fma_f64 v[112:113], v[112:113], s[84:85], -v[176:177]
	v_pk_mul_f32 v[178:179], v[0:1], v[210:211] op_sel_hi:[0,1]
	v_cvt_f64_f32_e32 v[210:211], v110
	v_cvt_f32_f64_e32 v176, v[112:113]
	v_pk_mul_f32 v[112:113], v[0:1], v[212:213] op_sel_hi:[0,1]
	v_mul_f64 v[212:213], v[210:211], s[84:85]
	v_rndne_f64_e32 v[212:213], v[212:213]
	v_fma_f64 v[210:211], v[210:211], s[84:85], -v[212:213]
	v_sin_f32_e32 v111, v176
	v_cos_f32_e32 v177, v176
	v_cvt_f32_f64_e32 v176, v[210:211]
	v_sin_f32_e32 v110, v176
	v_cos_f32_e32 v176, v176
	v_pk_mul_f32 v[6:7], v[6:7], v[178:179]
	v_pk_mul_f32 v[112:113], v[10:11], v[112:113]
	v_mul_f32_e32 v108, v108, v223
	v_pk_mul_f32 v[10:11], v[176:177], v[6:7]
	v_pk_mul_f32 v[6:7], v[110:111], v[6:7]
	v_pk_fma_f32 v[10:11], v[110:111], v[112:113], v[10:11]
	v_cvt_f64_f32_e32 v[110:111], v109
	v_pk_fma_f32 v[6:7], v[176:177], v[112:113], v[6:7] neg_lo:[0,0,1] neg_hi:[0,0,1]
	v_mul_f64 v[112:113], v[110:111], s[84:85]
	v_rndne_f64_e32 v[112:113], v[112:113]
	v_cvt_f64_f32_e32 v[178:179], v108
	v_fma_f64 v[110:111], v[110:111], s[84:85], -v[112:113]
	v_pk_mul_f32 v[112:113], v[0:1], v[206:207] op_sel_hi:[0,1]
	v_mul_f64 v[206:207], v[178:179], s[84:85]
	v_rndne_f64_e32 v[206:207], v[206:207]
	v_cvt_f32_f64_e32 v110, v[110:111]
	v_fma_f64 v[178:179], v[178:179], s[84:85], -v[206:207]
	v_sin_f32_e32 v109, v110
	v_cos_f32_e32 v111, v110
	v_cvt_f32_f64_e32 v110, v[178:179]
	v_sin_f32_e32 v108, v110
	v_cos_f32_e32 v110, v110
	v_pk_mul_f32 v[176:177], v[0:1], v[208:209] op_sel_hi:[0,1]
	v_pk_mul_f32 v[96:97], v[96:97], v[176:177]
	v_pk_mul_f32 v[92:93], v[92:93], v[112:113]
	v_pk_mul_f32 v[112:113], v[110:111], v[96:97]
	v_pk_mul_f32 v[96:97], v[108:109], v[96:97]
	v_pk_fma_f32 v[208:209], v[108:109], v[92:93], v[112:113]
	v_pk_fma_f32 v[206:207], v[110:111], v[92:93], v[96:97] neg_lo:[0,0,1] neg_hi:[0,0,1]
	v_mul_f32_e32 v92, v107, v223
	v_cvt_f64_f32_e32 v[92:93], v92
	v_mul_f64 v[96:97], v[92:93], s[84:85]
	v_rndne_f64_e32 v[96:97], v[96:97]
	v_fma_f64 v[92:93], v[92:93], s[84:85], -v[96:97]
	v_cvt_f32_f64_e32 v92, v[92:93]
	v_sin_f32_e32 v93, v92
	v_cos_f32_e32 v107, v92
	v_mul_f32_e32 v92, v106, v223
	v_cvt_f64_f32_e32 v[110:111], v92
	v_mul_f64 v[112:113], v[110:111], s[84:85]
	v_rndne_f64_e32 v[112:113], v[112:113]
	v_fma_f64 v[110:111], v[110:111], s[84:85], -v[112:113]
	v_cvt_f32_f64_e32 v106, v[110:111]
	v_sin_f32_e32 v92, v106
	v_cos_f32_e32 v106, v106
	v_pk_mul_f32 v[108:109], v[0:1], v[204:205] op_sel_hi:[0,1]
	v_pk_mul_f32 v[96:97], v[0:1], v[202:203] op_sel_hi:[0,1]
	v_pk_mul_f32 v[94:95], v[94:95], v[108:109]
	v_pk_mul_f32 v[90:91], v[90:91], v[96:97]
	v_pk_mul_f32 v[96:97], v[106:107], v[94:95]
	v_cvt_f64_f32_e32 v[178:179], v99
	v_pk_fma_f32 v[204:205], v[92:93], v[90:91], v[96:97]
	v_pk_mul_f32 v[92:93], v[92:93], v[94:95]
	v_mul_f32_e32 v100, v100, v223
	v_pk_fma_f32 v[202:203], v[106:107], v[90:91], v[92:93] neg_lo:[0,0,1] neg_hi:[0,0,1]
	v_mul_f32_e32 v90, v102, v223
	v_cvt_f64_f32_e32 v[90:91], v90
	v_mul_f64 v[92:93], v[90:91], s[84:85]
	v_rndne_f64_e32 v[92:93], v[92:93]
	v_fma_f64 v[90:91], v[90:91], s[84:85], -v[92:93]
	v_cvt_f32_f64_e32 v91, v[90:91]
	v_sin_f32_e32 v90, v91
	v_cos_f32_e32 v94, v91
	v_mul_f32_e32 v91, v103, v223
	v_cvt_f64_f32_e32 v[102:103], v91
	v_mul_f64 v[106:107], v[102:103], s[84:85]
	v_rndne_f64_e32 v[106:107], v[106:107]
	v_fma_f64 v[102:103], v[102:103], s[84:85], -v[106:107]
	v_cvt_f32_f64_e32 v95, v[102:103]
	v_mul_f32_e32 v102, v104, v223
	v_cvt_f64_f32_e32 v[102:103], v102
	v_mul_f64 v[106:107], v[102:103], s[84:85]
	v_rndne_f64_e32 v[106:107], v[106:107]
	v_fma_f64 v[102:103], v[102:103], s[84:85], -v[106:107]
	v_cvt_f32_f64_e32 v103, v[102:103]
	v_sin_f32_e32 v102, v103
	v_cos_f32_e32 v104, v103
	v_mul_f32_e32 v103, v105, v223
	v_cvt_f64_f32_e32 v[110:111], v103
	v_mul_f64 v[112:113], v[110:111], s[84:85]
	v_rndne_f64_e32 v[112:113], v[112:113]
	v_fma_f64 v[110:111], v[110:111], s[84:85], -v[112:113]
	v_pk_mul_f32 v[106:107], v[0:1], v[186:187] op_sel_hi:[0,1]
	v_cvt_f32_f64_e32 v105, v[110:111]
	v_cvt_f64_f32_e32 v[110:111], v98
	v_mul_f64 v[186:187], v[178:179], s[84:85]
	v_mul_f64 v[112:113], v[110:111], s[84:85]
	v_rndne_f64_e32 v[186:187], v[186:187]
	v_sin_f32_e32 v91, v95
	v_cos_f32_e32 v95, v95
	v_rndne_f64_e32 v[112:113], v[112:113]
	v_fma_f64 v[178:179], v[178:179], s[84:85], -v[186:187]
	v_mul_f32_e32 v101, v101, v223
	v_pk_mul_f32 v[108:109], v[0:1], v[190:191] op_sel_hi:[0,1]
	v_fma_f64 v[110:111], v[110:111], s[84:85], -v[112:113]
	v_cvt_f32_f64_e32 v113, v[178:179]
	v_cvt_f64_f32_e32 v[178:179], v100
	v_cvt_f64_f32_e32 v[190:191], v101
	v_pk_mul_f32 v[92:93], v[0:1], v[188:189] op_sel_hi:[0,1]
	v_pk_mul_f32 v[96:97], v[0:1], v[192:193] op_sel_hi:[0,1]
	v_sin_f32_e32 v103, v105
	v_cos_f32_e32 v105, v105
	v_mul_f64 v[186:187], v[178:179], s[84:85]
	v_mul_f64 v[192:193], v[190:191], s[84:85]
	v_cvt_f32_f64_e32 v112, v[110:111]
	v_rndne_f64_e32 v[186:187], v[186:187]
	v_rndne_f64_e32 v[192:193], v[192:193]
	v_pk_mul_f32 v[86:87], v[86:87], v[92:93]
	v_pk_mul_f32 v[92:93], v[82:83], v[96:97]
	v_sin_f32_e32 v98, v112
	v_cos_f32_e32 v112, v112
	v_sin_f32_e32 v99, v113
	v_cos_f32_e32 v113, v113
	v_fma_f64 v[178:179], v[178:179], s[84:85], -v[186:187]
	v_fma_f64 v[190:191], v[190:191], s[84:85], -v[192:193]
	v_pk_mul_f32 v[82:83], v[94:95], v[92:93]
	v_cvt_f32_f64_e32 v186, v[178:179]
	v_cvt_f32_f64_e32 v187, v[190:191]
	v_pk_fma_f32 v[82:83], v[90:91], v[86:87], v[82:83]
	v_pk_mul_f32 v[90:91], v[90:91], v[92:93]
	v_pk_mul_f32 v[84:85], v[84:85], v[108:109]
	v_pk_mul_f32 v[176:177], v[0:1], v[200:201] op_sel_hi:[0,1]
	v_sin_f32_e32 v100, v186
	v_cos_f32_e32 v186, v186
	v_sin_f32_e32 v101, v187
	v_cos_f32_e32 v187, v187
	v_pk_fma_f32 v[86:87], v[94:95], v[86:87], v[90:91] neg_lo:[0,0,1] neg_hi:[0,0,1]
	v_pk_mul_f32 v[88:89], v[88:89], v[106:107]
	v_pk_mul_f32 v[90:91], v[104:105], v[84:85]
	v_pk_mul_f32 v[84:85], v[102:103], v[84:85]
	v_pk_mul_f32 v[110:111], v[0:1], v[196:197] op_sel_hi:[0,1]
	v_pk_fma_f32 v[84:85], v[104:105], v[88:89], v[84:85] neg_lo:[0,0,1] neg_hi:[0,0,1]
	v_pk_mul_f32 v[74:75], v[74:75], v[176:177]
	v_pk_mul_f32 v[188:189], v[0:1], v[198:199] op_sel_hi:[0,1]
	v_cvt_pk_bf16_f32 v86, v86, v87
	v_cvt_pk_bf16_f32 v87, v84, v85
	v_pk_mul_f32 v[78:79], v[78:79], v[110:111]
	v_pk_mul_f32 v[84:85], v[112:113], v[74:75]
	v_pk_mul_f32 v[74:75], v[98:99], v[74:75]
	v_pk_mul_f32 v[178:179], v[0:1], v[194:195] op_sel_hi:[0,1]
	v_pk_fma_f32 v[74:75], v[112:113], v[78:79], v[74:75] neg_lo:[0,0,1] neg_hi:[0,0,1]
	v_pk_mul_f32 v[76:77], v[76:77], v[188:189]
	v_pk_fma_f32 v[90:91], v[102:103], v[88:89], v[90:91]
	v_pk_fma_f32 v[84:85], v[98:99], v[78:79], v[84:85]
	v_cvt_pk_bf16_f32 v88, v74, v75
	v_pk_mul_f32 v[74:75], v[80:81], v[178:179]
	v_pk_mul_f32 v[78:79], v[186:187], v[76:77]
	v_pk_mul_f32 v[76:77], v[100:101], v[76:77]
	v_pk_fma_f32 v[78:79], v[100:101], v[74:75], v[78:79]
	v_pk_fma_f32 v[74:75], v[186:187], v[74:75], v[76:77] neg_lo:[0,0,1] neg_hi:[0,0,1]
	v_cvt_pk_bf16_f32 v82, v82, v83
	v_cvt_pk_bf16_f32 v89, v74, v75
	v_pk_mul_f32 v[74:75], v[0:1], v[170:171] op_sel_hi:[0,1]
	v_pk_mul_f32 v[70:71], v[70:71], v[74:75]
	v_cvt_pk_bf16_f32 v83, v90, v91
	v_cvt_pk_bf16_f32 v90, v70, v71
	v_pk_mul_f32 v[70:71], v[0:1], v[172:173] op_sel_hi:[0,1]
	v_pk_mul_f32 v[70:71], v[72:73], v[70:71]
	v_cvt_pk_bf16_f32 v84, v84, v85
	v_cvt_pk_bf16_f32 v91, v70, v71
	v_pk_mul_f32 v[70:71], v[0:1], v[182:183] op_sel_hi:[0,1]
	v_pk_mul_f32 v[66:67], v[66:67], v[70:71]
	v_cvt_pk_bf16_f32 v85, v78, v79
	v_cvt_pk_bf16_f32 v92, v66, v67
	v_pk_mul_f32 v[66:67], v[0:1], v[184:185] op_sel_hi:[0,1]
	v_pk_mul_f32 v[66:67], v[68:69], v[66:67]
	s_nop 0
	v_cvt_pk_bf16_f32 v93, v66, v67
	v_pk_mul_f32 v[66:67], v[0:1], v[162:163] op_sel_hi:[0,1]
	v_pk_mul_f32 v[62:63], v[62:63], v[66:67]
	s_nop 0
	v_cvt_pk_bf16_f32 v94, v62, v63
	v_pk_mul_f32 v[62:63], v[0:1], v[166:167] op_sel_hi:[0,1]
	v_pk_mul_f32 v[62:63], v[64:65], v[62:63]
	s_nop 0
	v_cvt_pk_bf16_f32 v95, v62, v63
	v_pk_mul_f32 v[62:63], v[0:1], v[164:165] op_sel_hi:[0,1]
	v_pk_mul_f32 v[58:59], v[58:59], v[62:63]
	s_nop 0
	v_cvt_pk_bf16_f32 v96, v58, v59
	v_pk_mul_f32 v[58:59], v[0:1], v[168:169] op_sel_hi:[0,1]
	v_pk_mul_f32 v[58:59], v[60:61], v[58:59]
	s_nop 0
	v_cvt_pk_bf16_f32 v97, v58, v59
	v_pk_mul_f32 v[58:59], v[0:1], v[154:155] op_sel_hi:[0,1]
	v_pk_mul_f32 v[54:55], v[54:55], v[58:59]
	s_nop 0
	v_cvt_pk_bf16_f32 v98, v54, v55
	v_pk_mul_f32 v[54:55], v[0:1], v[160:161] op_sel_hi:[0,1]
	v_pk_mul_f32 v[54:55], v[56:57], v[54:55]
	s_nop 0
	v_cvt_pk_bf16_f32 v99, v54, v55
	v_pk_mul_f32 v[54:55], v[0:1], v[158:159] op_sel_hi:[0,1]
	v_pk_mul_f32 v[50:51], v[50:51], v[54:55]
	s_nop 0
	v_cvt_pk_bf16_f32 v100, v50, v51
	v_pk_mul_f32 v[50:51], v[0:1], v[156:157] op_sel_hi:[0,1]
	v_pk_mul_f32 v[50:51], v[52:53], v[50:51]
	s_nop 0
	v_cvt_pk_bf16_f32 v101, v50, v51
	v_pk_mul_f32 v[50:51], v[0:1], v[146:147] op_sel_hi:[0,1]
	v_pk_mul_f32 v[46:47], v[46:47], v[50:51]
	v_mov_b32_e32 v50, 0
	v_cvt_pk_bf16_f32 v102, v46, v47
	v_pk_mul_f32 v[46:47], v[0:1], v[148:149] op_sel_hi:[0,1]
	v_pk_mul_f32 v[46:47], v[48:49], v[46:47]
	s_nop 0
	v_cvt_pk_bf16_f32 v103, v46, v47
	v_pk_mul_f32 v[46:47], v[0:1], v[150:151] op_sel_hi:[0,1]
	v_pk_mul_f32 v[42:43], v[42:43], v[46:47]
	s_nop 0
	v_cvt_pk_bf16_f32 v104, v42, v43
	v_pk_mul_f32 v[42:43], v[0:1], v[152:153] op_sel_hi:[0,1]
	v_pk_mul_f32 v[42:43], v[44:45], v[42:43]
	s_nop 0
	v_cvt_pk_bf16_f32 v105, v42, v43
	v_pk_mul_f32 v[42:43], v[0:1], v[138:139] op_sel_hi:[0,1]
	v_pk_mul_f32 v[38:39], v[38:39], v[42:43]
	s_nop 0
	v_cvt_pk_bf16_f32 v106, v38, v39
	v_pk_mul_f32 v[38:39], v[0:1], v[140:141] op_sel_hi:[0,1]
	v_pk_mul_f32 v[38:39], v[40:41], v[38:39]
	s_nop 0
	v_cvt_pk_bf16_f32 v107, v38, v39
	v_pk_mul_f32 v[38:39], v[0:1], v[142:143] op_sel_hi:[0,1]
	v_pk_mul_f32 v[34:35], v[34:35], v[38:39]
	s_nop 0
	v_cvt_pk_bf16_f32 v108, v34, v35
	v_pk_mul_f32 v[34:35], v[0:1], v[144:145] op_sel_hi:[0,1]
	v_pk_mul_f32 v[34:35], v[36:37], v[34:35]
	s_nop 0
	v_cvt_pk_bf16_f32 v109, v34, v35
	v_pk_mul_f32 v[34:35], v[0:1], v[130:131] op_sel_hi:[0,1]
	v_pk_mul_f32 v[30:31], v[30:31], v[34:35]
	v_mov_b32_e32 v34, 0
	v_cvt_pk_bf16_f32 v110, v30, v31
	v_pk_mul_f32 v[30:31], v[0:1], v[132:133] op_sel_hi:[0,1]
	v_pk_mul_f32 v[30:31], v[32:33], v[30:31]
	s_nop 0
	v_cvt_pk_bf16_f32 v111, v30, v31
	v_pk_mul_f32 v[30:31], v[0:1], v[134:135] op_sel_hi:[0,1]
	v_pk_mul_f32 v[26:27], v[26:27], v[30:31]
	s_nop 0
	v_cvt_pk_bf16_f32 v112, v26, v27
	v_pk_mul_f32 v[26:27], v[0:1], v[136:137] op_sel_hi:[0,1]
	v_pk_mul_f32 v[26:27], v[28:29], v[26:27]
	s_nop 0
	v_cvt_pk_bf16_f32 v113, v26, v27
	v_pk_mul_f32 v[26:27], v[0:1], v[114:115] op_sel_hi:[0,1]
	v_pk_mul_f32 v[22:23], v[22:23], v[26:27]
	s_nop 0
	v_cvt_pk_bf16_f32 v114, v22, v23
	v_pk_mul_f32 v[22:23], v[0:1], v[116:117] op_sel_hi:[0,1]
	v_pk_mul_f32 v[22:23], v[24:25], v[22:23]
	s_nop 0
	v_cvt_pk_bf16_f32 v115, v22, v23
	v_pk_mul_f32 v[22:23], v[0:1], v[126:127] op_sel_hi:[0,1]
	v_pk_mul_f32 v[18:19], v[18:19], v[22:23]
	v_cvt_pk_bf16_f32 v126, v202, v203
	v_cvt_pk_bf16_f32 v116, v18, v19
	v_pk_mul_f32 v[18:19], v[0:1], v[128:129] op_sel_hi:[0,1]
	v_pk_mul_f32 v[18:19], v[20:21], v[18:19]
	v_cvt_pk_bf16_f32 v128, v6, v7
	v_cvt_pk_bf16_f32 v117, v18, v19
	v_pk_mul_f32 v[18:19], v[0:1], v[118:119] op_sel_hi:[0,1]
	v_pk_mul_f32 v[14:15], v[14:15], v[18:19]
	v_cvt_pk_bf16_f32 v127, v206, v207
	v_cvt_pk_bf16_f32 v118, v14, v15
	v_pk_mul_f32 v[14:15], v[0:1], v[120:121] op_sel_hi:[0,1]
	v_pk_mul_f32 v[14:15], v[16:17], v[14:15]
	v_mov_b32_e32 v18, 0
	v_cvt_pk_bf16_f32 v119, v14, v15
	v_pk_mul_f32 v[14:15], v[0:1], v[122:123] op_sel_hi:[0,1]
	v_pk_mul_f32 v[2:3], v[2:3], v[14:15]
	v_cvt_pk_bf16_f32 v122, v204, v205
	v_cvt_pk_bf16_f32 v120, v2, v3
	v_pk_mul_f32 v[2:3], v[0:1], v[124:125] op_sel_hi:[0,1]
	v_pk_mul_f32 v[2:3], v[4:5], v[2:3]
	v_pk_mul_f32 v[4:5], v[8:9], v[214:215]
	v_cvt_pk_bf16_f32 v121, v2, v3
	v_pk_mul_f32 v[2:3], v[12:13], v[216:217]
	v_pk_mul_f32 v[6:7], v[218:219], v[4:5]
	v_pk_mul_f32 v[4:5], v[220:221], v[4:5]
	v_pk_fma_f32 v[6:7], v[220:221], v[2:3], v[6:7]
	v_pk_fma_f32 v[2:3], v[218:219], v[2:3], v[4:5] neg_lo:[0,0,1] neg_hi:[0,0,1]
	v_mov_b32_e32 v0, 0
	v_cvt_pk_bf16_f32 v123, v208, v209
	v_cvt_pk_bf16_f32 v124, v10, v11
	v_cvt_pk_bf16_f32 v125, v6, v7
	v_cvt_pk_bf16_f32 v129, v2, v3
	v_mov_b32_e32 v2, 0
	v_mov_b32_e32 v3, v0
	v_mov_b32_e32 v4, v0
	v_mov_b32_e32 v5, v0
	v_mov_b32_e32 v6, v0
	v_mov_b32_e32 v7, v0
	v_mov_b32_e32 v8, v0
	v_mov_b32_e32 v9, v0
	v_mov_b32_e32 v10, v0
	v_mov_b32_e32 v11, v0
	v_mov_b32_e32 v12, v0
	v_mov_b32_e32 v13, v0
	v_mov_b32_e32 v14, v0
	v_mov_b32_e32 v15, v0
	v_mov_b32_e32 v16, v0
	v_mov_b32_e32 v17, v0
	v_mov_b32_e32 v19, v0
	v_mov_b32_e32 v20, v0
	v_mov_b32_e32 v21, v0
	v_mov_b32_e32 v22, v0
	v_mov_b32_e32 v23, v0
	v_mov_b32_e32 v24, v0
	v_mov_b32_e32 v25, v0
	v_mov_b32_e32 v26, v0
	v_mov_b32_e32 v27, v0
	v_mov_b32_e32 v28, v0
	v_mov_b32_e32 v29, v0
	v_mov_b32_e32 v30, v0
	v_mov_b32_e32 v31, v0
	v_mov_b32_e32 v32, v0
	v_mov_b32_e32 v33, v0
	v_mov_b32_e32 v35, v0
	v_mov_b32_e32 v36, v0
	v_mov_b32_e32 v37, v0
	v_mov_b32_e32 v38, v0
	v_mov_b32_e32 v39, v0
	v_mov_b32_e32 v40, v0
	v_mov_b32_e32 v41, v0
	v_mov_b32_e32 v42, v0
	v_mov_b32_e32 v43, v0
	v_mov_b32_e32 v44, v0
	v_mov_b32_e32 v45, v0
	v_mov_b32_e32 v46, v0
	v_mov_b32_e32 v47, v0
	v_mov_b32_e32 v48, v0
	v_mov_b32_e32 v49, v0
	v_mov_b32_e32 v51, v0
	v_mov_b32_e32 v52, v0
	v_mov_b32_e32 v53, v0
	v_mov_b32_e32 v54, v0
	v_mov_b32_e32 v55, v0
	v_mov_b32_e32 v56, v0
	v_mov_b32_e32 v57, v0
	v_mov_b32_e32 v58, v0
	v_mov_b32_e32 v59, v0
	v_mov_b32_e32 v60, v0
	v_mov_b32_e32 v61, v0
	v_mov_b32_e32 v62, v0
	v_mov_b32_e32 v63, v0
	v_mov_b32_e32 v64, v0
	v_mov_b32_e32 v65, v0
	v_mov_b32_e32 v208, v222
	v_lshlrev_b32_e32 v211, 3, v208
	v_lshrrev_b32_e32 v209, 1, v208
	v_lshlrev_b32_e32 v210, 7, v208
	v_and_b32_e32 v211, 8, v211
	v_ashrrev_i32_e32 v208, 5, v208
	v_add_u32_e32 v208, v211, v208
	v_and_b32_e32 v210, 0xf00, v210
	v_bitop3_b32 v211, v208, v209, 7 bitop3:0x78
	v_add_u32_e32 v212, 2, v208
	v_add_u32_e32 v213, 4, v208
	v_add_u32_e32 v208, 6, v208
	v_bitop3_b32 v212, v212, v209, 7 bitop3:0x78
	v_bitop3_b32 v213, v213, v209, 7 bitop3:0x78
	v_bitop3_b32 v208, v208, v209, 7 bitop3:0x78
	v_lshl_add_u32 v218, v211, 4, v210
	v_lshl_add_u32 v219, v212, 4, v210
	v_lshl_add_u32 v209, v213, 4, v210
	v_lshl_add_u32 v208, v208, 4, v210
	s_branch .LBB0_574

.LBB0_574:
	s_add_i32 s10, s33, 2
	s_cmp_ge_i32 s10, s21
	s_cselect_b64 s[22:23], -1, 0
	s_mov_b64 s[34:35], -1
	s_cmp_gt_i32 s33, s9
	s_cbranch_scc1 .Lat2_skip
	s_and_b64 vcc, exec, s[22:23]
	s_cbranch_vccnz .Lat2_nodma
	s_setprio 3
	s_mul_i32 s10, s28, 0xa000
	v_add_u32_e32 v198, s10, v218
	v_add_u32_e32 v199, s10, v219
	v_add_u32_e32 v200, s10, v209
	v_add_u32_e32 v201, s10, v208
	ds_read_b128 v[130:133], v198 offset:0
	ds_read_b128 v[134:137], v199 offset:0
	ds_read_b128 v[138:141], v200 offset:0
	ds_read_b128 v[142:145], v201 offset:0
	ds_read_b128 v[146:149], v198 offset:8192
	ds_read_b128 v[150:153], v199 offset:8192
	ds_read_b128 v[154:157], v200 offset:8192
	ds_read_b128 v[158:161], v201 offset:8192
	ds_read_b128 v[162:165], v198 offset:16384
	ds_read_b128 v[166:169], v199 offset:16384
	ds_read_b128 v[170:173], v200 offset:16384
	ds_read_b128 v[176:179], v201 offset:16384
	v_mad_u64_u32 v[204:205], s[10:11], s86, v228, v[174:175]
	s_mul_i32 s10, s7, 0xa000
	s_add_i32 s10, s0, s10
	s_mov_b32 m0, s10
	v_lshl_add_u64 v[206:207], v[204:205], 0, s[94:95]
	global_load_lds_dwordx4 v[204:205], off
	s_add_i32 m0, s10, 0x2000
	v_lshl_add_u64 v[204:205], v[204:205], 0, s[96:97]
	global_load_lds_dwordx4 v[206:207], off
	s_waitcnt lgkmcnt(8)
	v_mfma_f32_32x32x16_bf16 v[66:81], v[130:133], v[118:121], 0
	s_add_i32 m0, s10, 0x4000
	v_mfma_f32_32x32x16_bf16 v[66:81], v[134:137], v[114:117], v[66:81]
	global_load_lds_dwordx4 v[204:205], off
	v_lshl_add_u64 v[204:205], s[86:87], 1, v[180:181]
	s_add_i32 m0, s10, 0x6000
	v_mfma_f32_32x32x16_bf16 v[66:81], v[138:141], v[110:113], v[66:81]
	global_load_lds_dwordx4 v[204:205], off
	v_lshl_add_u64 v[204:205], v[204:205], 0, s[92:93]
	s_add_i32 m0, s10, 0x8000
	v_mfma_f32_32x32x16_bf16 v[66:81], v[142:145], v[106:109], v[66:81]
	global_load_lds_dwordx4 v[204:205], off
	ds_read_b128 v[130:133], v198 offset:4096
	ds_read_b128 v[134:137], v199 offset:4096
	ds_read_b128 v[138:141], v200 offset:4096
	ds_read_b128 v[142:145], v201 offset:4096
	s_waitcnt lgkmcnt(8)
	v_mfma_f32_32x32x16_bf16 v[66:81], v[146:149], v[102:105], v[66:81]
	v_mfma_f32_32x32x16_bf16 v[66:81], v[150:153], v[98:101], v[66:81]
	v_mfma_f32_32x32x16_bf16 v[66:81], v[154:157], v[94:97], v[66:81]
	v_mfma_f32_32x32x16_bf16 v[66:81], v[158:161], v[90:93], v[66:81]
	ds_read_b128 v[146:149], v198 offset:12288
	ds_read_b128 v[150:153], v199 offset:12288
	ds_read_b128 v[154:157], v200 offset:12288
	ds_read_b128 v[158:161], v201 offset:12288
	s_waitcnt lgkmcnt(8)
	v_mfma_f32_32x32x16_bf16 v[66:81], v[162:165], v[86:89], v[66:81]
	v_mfma_f32_32x32x16_bf16 v[66:81], v[166:169], v[126:129], v[66:81]
	v_mfma_f32_32x32x16_bf16 v[66:81], v[170:173], v[82:85], v[66:81]
	v_mfma_f32_32x32x16_bf16 v[66:81], v[176:179], v[122:125], v[66:81]
	s_setprio 2
	ds_read_b128 v[162:165], v198 offset:20480
	ds_read_b128 v[166:169], v199 offset:20480
	ds_read_b128 v[170:173], v200 offset:20480
	ds_read_b128 v[176:179], v201 offset:20480
	s_waitcnt lgkmcnt(8)
	v_mfma_f32_32x32x16_bf16 v[182:197], v[130:133], v[118:121], 0
	v_mfma_f32_32x32x16_bf16 v[182:197], v[134:137], v[114:117], v[182:197]
	v_mfma_f32_32x32x16_bf16 v[182:197], v[138:141], v[110:113], v[182:197]
	v_mfma_f32_32x32x16_bf16 v[182:197], v[142:145], v[106:109], v[182:197]
	ds_read_b128 v[130:133], v198 offset:24576
	ds_read_b128 v[134:137], v198 offset:28672
	ds_read_b128 v[138:141], v198 offset:32768
	ds_read_b128 v[142:145], v198 offset:36864
	s_waitcnt lgkmcnt(8)
	v_mfma_f32_32x32x16_bf16 v[182:197], v[146:149], v[102:105], v[182:197]
	v_med3_f32 v66, v66, s4, v236
	v_exp_f32_e32 v66, v66
	v_med3_f32 v67, v67, s4, v236
	v_exp_f32_e32 v67, v67
	v_mfma_f32_32x32x16_bf16 v[182:197], v[150:153], v[98:101], v[182:197]
	v_med3_f32 v68, v68, s4, v236
	v_exp_f32_e32 v68, v68
	v_med3_f32 v69, v69, s4, v236
	v_exp_f32_e32 v69, v69
	v_mfma_f32_32x32x16_bf16 v[182:197], v[154:157], v[94:97], v[182:197]
	v_med3_f32 v70, v70, s4, v236
	v_exp_f32_e32 v70, v70
	v_med3_f32 v71, v71, s4, v236
	v_exp_f32_e32 v71, v71
	v_mfma_f32_32x32x16_bf16 v[182:197], v[158:161], v[90:93], v[182:197]
	v_med3_f32 v72, v72, s4, v236
	v_exp_f32_e32 v72, v72
	v_med3_f32 v73, v73, s4, v236
	v_exp_f32_e32 v73, v73
	ds_read_b128 v[146:149], v199 offset:24576
	ds_read_b128 v[150:153], v199 offset:28672
	ds_read_b128 v[154:157], v199 offset:32768
	ds_read_b128 v[158:161], v199 offset:36864
	s_waitcnt lgkmcnt(8)
	v_mfma_f32_32x32x16_bf16 v[182:197], v[162:165], v[86:89], v[182:197]
	v_med3_f32 v74, v74, s4, v236
	v_exp_f32_e32 v74, v74
	v_med3_f32 v75, v75, s4, v236
	v_exp_f32_e32 v75, v75
	v_add_f32_e32 v202, v66, v67
	v_add_f32_e32 v202, v202, v68
	v_mfma_f32_32x32x16_bf16 v[182:197], v[166:169], v[126:129], v[182:197]
	v_med3_f32 v76, v76, s4, v236
	v_exp_f32_e32 v76, v76
	v_med3_f32 v77, v77, s4, v236
	v_exp_f32_e32 v77, v77
	v_add_f32_e32 v202, v202, v69
	v_add_f32_e32 v202, v202, v70
	v_mfma_f32_32x32x16_bf16 v[182:197], v[170:173], v[82:85], v[182:197]
	v_med3_f32 v78, v78, s4, v236
	v_exp_f32_e32 v78, v78
	v_med3_f32 v79, v79, s4, v236
	v_exp_f32_e32 v79, v79
	v_add_f32_e32 v202, v202, v71
	v_add_f32_e32 v202, v202, v72
	v_mfma_f32_32x32x16_bf16 v[182:197], v[176:179], v[122:125], v[182:197]
	v_med3_f32 v80, v80, s4, v236
	v_exp_f32_e32 v80, v80
	v_med3_f32 v81, v81, s4, v236
	v_exp_f32_e32 v81, v81
	v_add_f32_e32 v202, v202, v73
	s_setprio 1
	ds_read_b128 v[162:165], v200 offset:24576
	ds_read_b128 v[166:169], v200 offset:28672
	ds_read_b128 v[170:173], v200 offset:32768
	ds_read_b128 v[176:179], v200 offset:36864
	v_cvt_pk_bf16_f32 v66, v66, v67
	v_cvt_pk_bf16_f32 v67, v68, v69
	v_cvt_pk_bf16_f32 v68, v70, v71
	v_cvt_pk_bf16_f32 v69, v72, v73
	v_add_f32_e32 v202, v202, v74
	v_add_f32_e32 v202, v202, v75
	s_waitcnt lgkmcnt(8)
	v_mfma_f32_32x32x16_bf16 v[50:65], v[66:69], v[130:133], v[50:65]
	v_med3_f32 v182, v182, s4, v236
	v_exp_f32_e32 v182, v182
	v_med3_f32 v183, v183, s4, v236
	v_exp_f32_e32 v183, v183
	v_add_f32_e32 v202, v202, v76
	v_add_f32_e32 v202, v202, v77
	v_mfma_f32_32x32x16_bf16 v[34:49], v[66:69], v[134:137], v[34:49]
	v_med3_f32 v184, v184, s4, v236
	v_exp_f32_e32 v184, v184
	v_med3_f32 v185, v185, s4, v236
	v_exp_f32_e32 v185, v185
	v_add_f32_e32 v202, v202, v78
	v_add_f32_e32 v202, v202, v79
	v_mfma_f32_32x32x16_bf16 v[18:33], v[66:69], v[138:141], v[18:33]
	v_med3_f32 v186, v186, s4, v236
	v_exp_f32_e32 v186, v186
	v_med3_f32 v187, v187, s4, v236
	v_exp_f32_e32 v187, v187
	v_add_f32_e32 v202, v202, v80
	v_add_f32_e32 v202, v202, v81
	v_mfma_f32_32x32x16_bf16 v[2:17], v[66:69], v[142:145], v[2:17]
	v_med3_f32 v188, v188, s4, v236
	v_exp_f32_e32 v188, v188
	v_med3_f32 v189, v189, s4, v236
	v_exp_f32_e32 v189, v189
	v_cvt_pk_bf16_f32 v70, v74, v75
	v_cvt_pk_bf16_f32 v71, v76, v77
	v_cvt_pk_bf16_f32 v72, v78, v79
	v_cvt_pk_bf16_f32 v73, v80, v81
	ds_read_b128 v[130:133], v201 offset:24576
	ds_read_b128 v[134:137], v201 offset:28672
	ds_read_b128 v[138:141], v201 offset:32768
	ds_read_b128 v[142:145], v201 offset:36864
	s_waitcnt lgkmcnt(8)
	v_mfma_f32_32x32x16_bf16 v[50:65], v[70:73], v[146:149], v[50:65]
	v_med3_f32 v190, v190, s4, v236
	v_exp_f32_e32 v190, v190
	v_med3_f32 v191, v191, s4, v236
	v_exp_f32_e32 v191, v191
	v_add_f32_e32 v203, v182, v183
	v_add_f32_e32 v203, v203, v184
	v_mfma_f32_32x32x16_bf16 v[34:49], v[70:73], v[150:153], v[34:49]
	v_med3_f32 v192, v192, s4, v236
	v_exp_f32_e32 v192, v192
	v_med3_f32 v193, v193, s4, v236
	v_exp_f32_e32 v193, v193
	v_add_f32_e32 v203, v203, v185
	v_add_f32_e32 v203, v203, v186
	v_mfma_f32_32x32x16_bf16 v[18:33], v[70:73], v[154:157], v[18:33]
	v_med3_f32 v194, v194, s4, v236
	v_exp_f32_e32 v194, v194
	v_med3_f32 v195, v195, s4, v236
	v_exp_f32_e32 v195, v195
	v_add_f32_e32 v203, v203, v187
	v_mfma_f32_32x32x16_bf16 v[2:17], v[70:73], v[158:161], v[2:17]
	v_med3_f32 v196, v196, s4, v236
	v_exp_f32_e32 v196, v196
	v_med3_f32 v197, v197, s4, v236
	v_exp_f32_e32 v197, v197
	v_add_f32_e32 v203, v203, v188
	v_cvt_pk_bf16_f32 v182, v182, v183
	v_cvt_pk_bf16_f32 v183, v184, v185
	v_cvt_pk_bf16_f32 v184, v186, v187
	v_cvt_pk_bf16_f32 v185, v188, v189
	v_add_f32_e32 v203, v203, v189
	s_setprio 0
	s_waitcnt lgkmcnt(4)
	v_mfma_f32_32x32x16_bf16 v[50:65], v[182:185], v[162:165], v[50:65]
	v_add_f32_e32 v203, v203, v190
	v_add_f32_e32 v203, v203, v191
	v_add_f32_e32 v203, v203, v192
	v_mfma_f32_32x32x16_bf16 v[34:49], v[182:185], v[166:169], v[34:49]
	v_add_f32_e32 v203, v203, v193
	v_add_f32_e32 v203, v203, v194
	v_add_f32_e32 v203, v203, v195
	v_mfma_f32_32x32x16_bf16 v[18:33], v[182:185], v[170:173], v[18:33]
	v_add_f32_e32 v203, v203, v196
	v_add_f32_e32 v203, v203, v197
	v_cvt_pk_bf16_f32 v186, v190, v191
	v_cvt_pk_bf16_f32 v187, v192, v193
	v_cvt_pk_bf16_f32 v188, v194, v195
	v_cvt_pk_bf16_f32 v189, v196, v197
	v_mfma_f32_32x32x16_bf16 v[2:17], v[182:185], v[176:179], v[2:17]
	v_add_f32_e32 v202, v202, v203
	v_add_f32_e32 v0, v0, v202
	s_waitcnt lgkmcnt(0)
	v_mfma_f32_32x32x16_bf16 v[50:65], v[186:189], v[130:133], v[50:65]
	v_mfma_f32_32x32x16_bf16 v[34:49], v[186:189], v[134:137], v[34:49]
	v_mfma_f32_32x32x16_bf16 v[18:33], v[186:189], v[138:141], v[18:33]
	v_mfma_f32_32x32x16_bf16 v[2:17], v[186:189], v[142:145], v[2:17]
	s_waitcnt vmcnt(5) lgkmcnt(0)
	s_branch .LBB0_573
.Lat2_nodma:
	s_setprio 3
	s_mul_i32 s10, s28, 0xa000
	v_add_u32_e32 v198, s10, v218
	v_add_u32_e32 v199, s10, v219
	v_add_u32_e32 v200, s10, v209
	v_add_u32_e32 v201, s10, v208
	ds_read_b128 v[130:133], v198 offset:0
	ds_read_b128 v[134:137], v199 offset:0
	ds_read_b128 v[138:141], v200 offset:0
	ds_read_b128 v[142:145], v201 offset:0
	ds_read_b128 v[146:149], v198 offset:8192
	ds_read_b128 v[150:153], v199 offset:8192
	ds_read_b128 v[154:157], v200 offset:8192
	ds_read_b128 v[158:161], v201 offset:8192
	ds_read_b128 v[162:165], v198 offset:16384
	ds_read_b128 v[166:169], v199 offset:16384
	ds_read_b128 v[170:173], v200 offset:16384
	ds_read_b128 v[176:179], v201 offset:16384
	s_waitcnt lgkmcnt(8)
	v_mfma_f32_32x32x16_bf16 v[66:81], v[130:133], v[118:121], 0
	v_mfma_f32_32x32x16_bf16 v[66:81], v[134:137], v[114:117], v[66:81]
	v_mfma_f32_32x32x16_bf16 v[66:81], v[138:141], v[110:113], v[66:81]
	v_mfma_f32_32x32x16_bf16 v[66:81], v[142:145], v[106:109], v[66:81]
	ds_read_b128 v[130:133], v198 offset:4096
	ds_read_b128 v[134:137], v199 offset:4096
	ds_read_b128 v[138:141], v200 offset:4096
	ds_read_b128 v[142:145], v201 offset:4096
	s_waitcnt lgkmcnt(8)
	v_mfma_f32_32x32x16_bf16 v[66:81], v[146:149], v[102:105], v[66:81]
	v_mfma_f32_32x32x16_bf16 v[66:81], v[150:153], v[98:101], v[66:81]
	v_mfma_f32_32x32x16_bf16 v[66:81], v[154:157], v[94:97], v[66:81]
	v_mfma_f32_32x32x16_bf16 v[66:81], v[158:161], v[90:93], v[66:81]
	ds_read_b128 v[146:149], v198 offset:12288
	ds_read_b128 v[150:153], v199 offset:12288
	ds_read_b128 v[154:157], v200 offset:12288
	ds_read_b128 v[158:161], v201 offset:12288
	s_waitcnt lgkmcnt(8)
	v_mfma_f32_32x32x16_bf16 v[66:81], v[162:165], v[86:89], v[66:81]
	v_mfma_f32_32x32x16_bf16 v[66:81], v[166:169], v[126:129], v[66:81]
	v_mfma_f32_32x32x16_bf16 v[66:81], v[170:173], v[82:85], v[66:81]
	v_mfma_f32_32x32x16_bf16 v[66:81], v[176:179], v[122:125], v[66:81]
	s_setprio 2
	ds_read_b128 v[162:165], v198 offset:20480
	ds_read_b128 v[166:169], v199 offset:20480
	ds_read_b128 v[170:173], v200 offset:20480
	ds_read_b128 v[176:179], v201 offset:20480
	s_waitcnt lgkmcnt(8)
	v_mfma_f32_32x32x16_bf16 v[182:197], v[130:133], v[118:121], 0
	v_mfma_f32_32x32x16_bf16 v[182:197], v[134:137], v[114:117], v[182:197]
	v_mfma_f32_32x32x16_bf16 v[182:197], v[138:141], v[110:113], v[182:197]
	v_mfma_f32_32x32x16_bf16 v[182:197], v[142:145], v[106:109], v[182:197]
	ds_read_b128 v[130:133], v198 offset:24576
	ds_read_b128 v[134:137], v198 offset:28672
	ds_read_b128 v[138:141], v198 offset:32768
	ds_read_b128 v[142:145], v198 offset:36864
	s_waitcnt lgkmcnt(8)
	v_mfma_f32_32x32x16_bf16 v[182:197], v[146:149], v[102:105], v[182:197]
	v_med3_f32 v66, v66, s4, v236
	v_exp_f32_e32 v66, v66
	v_med3_f32 v67, v67, s4, v236
	v_exp_f32_e32 v67, v67
	v_mfma_f32_32x32x16_bf16 v[182:197], v[150:153], v[98:101], v[182:197]
	v_med3_f32 v68, v68, s4, v236
	v_exp_f32_e32 v68, v68
	v_med3_f32 v69, v69, s4, v236
	v_exp_f32_e32 v69, v69
	v_mfma_f32_32x32x16_bf16 v[182:197], v[154:157], v[94:97], v[182:197]
	v_med3_f32 v70, v70, s4, v236
	v_exp_f32_e32 v70, v70
	v_med3_f32 v71, v71, s4, v236
	v_exp_f32_e32 v71, v71
	v_mfma_f32_32x32x16_bf16 v[182:197], v[158:161], v[90:93], v[182:197]
	v_med3_f32 v72, v72, s4, v236
	v_exp_f32_e32 v72, v72
	v_med3_f32 v73, v73, s4, v236
	v_exp_f32_e32 v73, v73
	ds_read_b128 v[146:149], v199 offset:24576
	ds_read_b128 v[150:153], v199 offset:28672
	ds_read_b128 v[154:157], v199 offset:32768
	ds_read_b128 v[158:161], v199 offset:36864
	s_waitcnt lgkmcnt(8)
	v_mfma_f32_32x32x16_bf16 v[182:197], v[162:165], v[86:89], v[182:197]
	v_med3_f32 v74, v74, s4, v236
	v_exp_f32_e32 v74, v74
	v_med3_f32 v75, v75, s4, v236
	v_exp_f32_e32 v75, v75
	v_add_f32_e32 v202, v66, v67
	v_add_f32_e32 v202, v202, v68
	v_mfma_f32_32x32x16_bf16 v[182:197], v[166:169], v[126:129], v[182:197]
	v_med3_f32 v76, v76, s4, v236
	v_exp_f32_e32 v76, v76
	v_med3_f32 v77, v77, s4, v236
	v_exp_f32_e32 v77, v77
	v_add_f32_e32 v202, v202, v69
	v_add_f32_e32 v202, v202, v70
	v_mfma_f32_32x32x16_bf16 v[182:197], v[170:173], v[82:85], v[182:197]
	v_med3_f32 v78, v78, s4, v236
	v_exp_f32_e32 v78, v78
	v_med3_f32 v79, v79, s4, v236
	v_exp_f32_e32 v79, v79
	v_add_f32_e32 v202, v202, v71
	v_add_f32_e32 v202, v202, v72
	v_mfma_f32_32x32x16_bf16 v[182:197], v[176:179], v[122:125], v[182:197]
	v_med3_f32 v80, v80, s4, v236
	v_exp_f32_e32 v80, v80
	v_med3_f32 v81, v81, s4, v236
	v_exp_f32_e32 v81, v81
	v_add_f32_e32 v202, v202, v73
	s_setprio 1
	ds_read_b128 v[162:165], v200 offset:24576
	ds_read_b128 v[166:169], v200 offset:28672
	ds_read_b128 v[170:173], v200 offset:32768
	ds_read_b128 v[176:179], v200 offset:36864
	v_cvt_pk_bf16_f32 v66, v66, v67
	v_cvt_pk_bf16_f32 v67, v68, v69
	v_cvt_pk_bf16_f32 v68, v70, v71
	v_cvt_pk_bf16_f32 v69, v72, v73
	v_add_f32_e32 v202, v202, v74
	v_add_f32_e32 v202, v202, v75
	s_waitcnt lgkmcnt(8)
	v_mfma_f32_32x32x16_bf16 v[50:65], v[66:69], v[130:133], v[50:65]
	v_med3_f32 v182, v182, s4, v236
	v_exp_f32_e32 v182, v182
	v_med3_f32 v183, v183, s4, v236
	v_exp_f32_e32 v183, v183
	v_add_f32_e32 v202, v202, v76
	v_add_f32_e32 v202, v202, v77
	v_mfma_f32_32x32x16_bf16 v[34:49], v[66:69], v[134:137], v[34:49]
	v_med3_f32 v184, v184, s4, v236
	v_exp_f32_e32 v184, v184
	v_med3_f32 v185, v185, s4, v236
	v_exp_f32_e32 v185, v185
	v_add_f32_e32 v202, v202, v78
	v_add_f32_e32 v202, v202, v79
	v_mfma_f32_32x32x16_bf16 v[18:33], v[66:69], v[138:141], v[18:33]
	v_med3_f32 v186, v186, s4, v236
	v_exp_f32_e32 v186, v186
	v_med3_f32 v187, v187, s4, v236
	v_exp_f32_e32 v187, v187
	v_add_f32_e32 v202, v202, v80
	v_add_f32_e32 v202, v202, v81
	v_mfma_f32_32x32x16_bf16 v[2:17], v[66:69], v[142:145], v[2:17]
	v_med3_f32 v188, v188, s4, v236
	v_exp_f32_e32 v188, v188
	v_med3_f32 v189, v189, s4, v236
	v_exp_f32_e32 v189, v189
	v_cvt_pk_bf16_f32 v70, v74, v75
	v_cvt_pk_bf16_f32 v71, v76, v77
	v_cvt_pk_bf16_f32 v72, v78, v79
	v_cvt_pk_bf16_f32 v73, v80, v81
	ds_read_b128 v[130:133], v201 offset:24576
	ds_read_b128 v[134:137], v201 offset:28672
	ds_read_b128 v[138:141], v201 offset:32768
	ds_read_b128 v[142:145], v201 offset:36864
	s_waitcnt lgkmcnt(8)
	v_mfma_f32_32x32x16_bf16 v[50:65], v[70:73], v[146:149], v[50:65]
	v_med3_f32 v190, v190, s4, v236
	v_exp_f32_e32 v190, v190
	v_med3_f32 v191, v191, s4, v236
	v_exp_f32_e32 v191, v191
	v_add_f32_e32 v203, v182, v183
	v_add_f32_e32 v203, v203, v184
	v_mfma_f32_32x32x16_bf16 v[34:49], v[70:73], v[150:153], v[34:49]
	v_med3_f32 v192, v192, s4, v236
	v_exp_f32_e32 v192, v192
	v_med3_f32 v193, v193, s4, v236
	v_exp_f32_e32 v193, v193
	v_add_f32_e32 v203, v203, v185
	v_add_f32_e32 v203, v203, v186
	v_mfma_f32_32x32x16_bf16 v[18:33], v[70:73], v[154:157], v[18:33]
	v_med3_f32 v194, v194, s4, v236
	v_exp_f32_e32 v194, v194
	v_med3_f32 v195, v195, s4, v236
	v_exp_f32_e32 v195, v195
	v_add_f32_e32 v203, v203, v187
	v_mfma_f32_32x32x16_bf16 v[2:17], v[70:73], v[158:161], v[2:17]
	v_med3_f32 v196, v196, s4, v236
	v_exp_f32_e32 v196, v196
	v_med3_f32 v197, v197, s4, v236
	v_exp_f32_e32 v197, v197
	v_add_f32_e32 v203, v203, v188
	v_cvt_pk_bf16_f32 v182, v182, v183
	v_cvt_pk_bf16_f32 v183, v184, v185
	v_cvt_pk_bf16_f32 v184, v186, v187
	v_cvt_pk_bf16_f32 v185, v188, v189
	v_add_f32_e32 v203, v203, v189
	s_setprio 0
	s_waitcnt lgkmcnt(4)
	v_mfma_f32_32x32x16_bf16 v[50:65], v[182:185], v[162:165], v[50:65]
	v_add_f32_e32 v203, v203, v190
	v_add_f32_e32 v203, v203, v191
	v_add_f32_e32 v203, v203, v192
	v_mfma_f32_32x32x16_bf16 v[34:49], v[182:185], v[166:169], v[34:49]
	v_add_f32_e32 v203, v203, v193
	v_add_f32_e32 v203, v203, v194
	v_add_f32_e32 v203, v203, v195
	v_mfma_f32_32x32x16_bf16 v[18:33], v[182:185], v[170:173], v[18:33]
	v_add_f32_e32 v203, v203, v196
	v_add_f32_e32 v203, v203, v197
	v_cvt_pk_bf16_f32 v186, v190, v191
	v_cvt_pk_bf16_f32 v187, v192, v193
	v_cvt_pk_bf16_f32 v188, v194, v195
	v_cvt_pk_bf16_f32 v189, v196, v197
	v_mfma_f32_32x32x16_bf16 v[2:17], v[182:185], v[176:179], v[2:17]
	v_add_f32_e32 v202, v202, v203
	v_add_f32_e32 v0, v0, v202
	s_waitcnt lgkmcnt(0)
	v_mfma_f32_32x32x16_bf16 v[50:65], v[186:189], v[130:133], v[50:65]
	v_mfma_f32_32x32x16_bf16 v[34:49], v[186:189], v[134:137], v[34:49]
	v_mfma_f32_32x32x16_bf16 v[18:33], v[186:189], v[138:141], v[18:33]
	v_mfma_f32_32x32x16_bf16 v[2:17], v[186:189], v[142:145], v[2:17]
	s_waitcnt vmcnt(0) lgkmcnt(0)
	s_branch .LBB0_573
